# GEMM K-loops: removed the s_setprio 0/1 pair in the middle of each 32-MFMA block
# speedup vs baseline: 1.0251x; 1.0251x over previous
; #define PG8_STAGE(bufoff, gbase, voff) do { _Pragma("unroll") for (int _i = 0; _i < 2; ++_i) \
;         __builtin_amdgcn_global_load_lds((const unsigned*)((const char*)(gbase) + (voff)[_i]), (PG8_LAS unsigned*)(lds + (bufoff) + ldsw + _i * 8192), 16, 0, 0); } while (0)
; #define PG8_LDA(dst, b, h) do { _Pragma("unroll") for (int m = 0; m < 4; ++m) _Pragma("unroll") for (int k = 0; k < 2; ++k) dst[m][k] = *(const PG8_LAS bf16x8*)(lds + PG8_SA(b, h) + aoff + m * 2048 + k * 1024); } while (0)
; #define PG8_LDB(dst, b, h) do { _Pragma("unroll") for (int n = 0; n < 2; ++n) _Pragma("unroll") for (int k = 0; k < 2; ++k) dst[n][k] = *(const PG8_LAS bf16x8*)(lds + PG8_SB(b, h) + boff + n * 2048 + k * 1024); } while (0)
; #define PG8_MMA(ai, bj, At, Bt) do { __builtin_amdgcn_s_setprio(1); _Pragma("unroll") for (int m = 0; m < 4; ++m) _Pragma("unroll") for (int n = 0; n < 2; ++n) _Pragma("unroll") for (int k = 0; k < 2; ++k) \
;         acc[ai][bj][m][n] = __builtin_amdgcn_mfma_f32_16x16x32_bf16(Bt[n][k], At[m][k], acc[ai][bj][m][n], 0, 0, 0); __builtin_amdgcn_s_setprio(0); } while (0)
; #define PG8_WAIT_V(n) asm volatile("s_waitcnt vmcnt(" #n ")" ::: "memory")
; #define PG8_WAIT_L(n) asm volatile("s_waitcnt lgkmcnt(" #n ")" ::: "memory")
; #define PG8_BAR __builtin_amdgcn_s_barrier()
; #define PG8_SCHED __builtin_amdgcn_sched_barrier(0)
; template <class Epi, class Sched, bool ALIGN_EPI = false, bool SP2 = false>
; __device__ __forceinline__ void gemm_phase(PG8_LAS unsigned char* lds, const Gemm g, const Sched& S, const Epi& E) {
;     ...
;             PG8_LDB(B0, 0, 0); PG8_LDB(B1, 0, 1); PG8_SCHED; PG8_LDA(At, 0, 0); PG8_STAGE(PG8_SA(1, 1), a1 + hstep, voffA);
;             PG8_WAIT_V(8); PG8_WAIT_L(0); PG8_BAR; PG8_MMA(0, 0, At, B0); PG8_MMA(0, 1, At, B1); PG8_BAR; PG8_SCHED;
;             PG8_LDA(At, 0, 1); PG8_STAGE(PG8_SB(0, 0), b2, voffB); PG8_STAGE(PG8_SB(0, 1), b2 + hstep, voffB); PG8_STAGE(PG8_SA(0, 0), a2, voffA);
.LBB0_252:
	s_add_u32 s12, s56, 0xfffc0080
	s_addc_u32 s13, s57, -1
	s_add_i32 s14, 0, 0x10000
	s_cmp_eq_u32 s10, 12
	s_cselect_b32 s67, s45, s13
	s_cselect_b32 s66, s61, s12
	v_add_u32_e32 v152, s14, v133
	s_cselect_b32 s59, s53, s2
	s_cselect_b32 s58, vcc_lo, vcc_hi
	s_add_i32 s15, 0, 0x14000
	ds_read_b128 v[162:165], v152
	ds_read_b128 v[166:169], v152 offset:1024
	ds_read_b128 v[170:173], v152 offset:2048
	ds_read_b128 v[174:177], v152 offset:3072
	v_add_u32_e32 v152, s15, v133
	ds_read_b128 v[178:181], v152
	ds_read_b128 v[182:185], v152 offset:1024
	ds_read_b128 v[186:189], v152 offset:2048
	ds_read_b128 v[190:193], v152 offset:3072
	v_lshl_add_u64 v[152:153], s[56:57], 0, v[148:149]
	s_add_i32 m0, s11, 0xc000
	ds_read_b128 v[194:197], v158
	ds_read_b128 v[198:201], v158 offset:1024
	ds_read_b128 v[202:205], v158 offset:2048
	ds_read_b128 v[206:209], v158 offset:3072
	ds_read_b128 v[210:213], v158 offset:4096
	ds_read_b128 v[214:217], v158 offset:5120
	ds_read_b128 v[218:221], v158 offset:6144
	ds_read_b128 v[222:225], v158 offset:7168
	global_load_lds_dwordx4 v[152:153], off
	v_lshl_add_u64 v[152:153], s[56:57], 0, v[150:151]
	s_add_i32 m0, s11, 0xe000
	s_nop 0
	global_load_lds_dwordx4 v[152:153], off
	s_waitcnt vmcnt(8)
	s_waitcnt lgkmcnt(0)
	s_barrier
	s_setprio 1
	s_waitcnt lgkmcnt(0)
	v_mfma_f32_16x16x32_bf16 v[126:129], v[162:165], v[194:197], v[126:129]
	v_mfma_f32_16x16x32_bf16 v[122:125], v[170:173], v[194:197], v[122:125]
	v_mfma_f32_16x16x32_bf16 v[114:117], v[162:165], v[202:205], v[114:117]
	v_mfma_f32_16x16x32_bf16 v[106:109], v[170:173], v[202:205], v[106:109]
	v_mfma_f32_16x16x32_bf16 v[98:101], v[162:165], v[210:213], v[98:101]
	v_mfma_f32_16x16x32_bf16 v[90:93], v[170:173], v[210:213], v[90:93]
	v_mfma_f32_16x16x32_bf16 v[82:85], v[162:165], v[218:221], v[82:85]
	v_mfma_f32_16x16x32_bf16 v[74:77], v[170:173], v[218:221], v[74:77]
	v_mfma_f32_16x16x32_bf16 v[126:129], v[166:169], v[198:201], v[126:129]
	v_mfma_f32_16x16x32_bf16 v[122:125], v[174:177], v[198:201], v[122:125]
	v_mfma_f32_16x16x32_bf16 v[114:117], v[166:169], v[206:209], v[114:117]
	v_mfma_f32_16x16x32_bf16 v[106:109], v[174:177], v[206:209], v[106:109]
	v_mfma_f32_16x16x32_bf16 v[98:101], v[166:169], v[214:217], v[98:101]
	v_mfma_f32_16x16x32_bf16 v[90:93], v[174:177], v[214:217], v[90:93]
	v_mfma_f32_16x16x32_bf16 v[82:85], v[166:169], v[222:225], v[82:85]
	v_mfma_f32_16x16x32_bf16 v[74:77], v[174:177], v[222:225], v[74:77]
	v_mfma_f32_16x16x32_bf16 v[118:121], v[178:181], v[194:197], v[118:121]
	v_mfma_f32_16x16x32_bf16 v[110:113], v[186:189], v[194:197], v[110:113]
	v_mfma_f32_16x16x32_bf16 v[102:105], v[178:181], v[202:205], v[102:105]
	v_mfma_f32_16x16x32_bf16 v[94:97], v[186:189], v[202:205], v[94:97]
	v_mfma_f32_16x16x32_bf16 v[86:89], v[178:181], v[210:213], v[86:89]
	v_mfma_f32_16x16x32_bf16 v[78:81], v[186:189], v[210:213], v[78:81]
	v_mfma_f32_16x16x32_bf16 v[70:73], v[178:181], v[218:221], v[70:73]
	v_mfma_f32_16x16x32_bf16 v[66:69], v[186:189], v[218:221], v[66:69]
	v_mfma_f32_16x16x32_bf16 v[118:121], v[182:185], v[198:201], v[118:121]
	v_mfma_f32_16x16x32_bf16 v[110:113], v[190:193], v[198:201], v[110:113]
	v_mfma_f32_16x16x32_bf16 v[102:105], v[182:185], v[206:209], v[102:105]
	v_mfma_f32_16x16x32_bf16 v[94:97], v[190:193], v[206:209], v[94:97]
	v_mfma_f32_16x16x32_bf16 v[86:89], v[182:185], v[214:217], v[86:89]
	v_mfma_f32_16x16x32_bf16 v[78:81], v[190:193], v[214:217], v[78:81]
	v_mfma_f32_16x16x32_bf16 v[70:73], v[182:185], v[222:225], v[70:73]
	v_mfma_f32_16x16x32_bf16 v[66:69], v[190:193], v[222:225], v[66:69]
	s_setprio 0
	s_barrier
	s_add_i32 s12, s14, s50
	v_lshl_add_u64 v[152:153], s[58:59], 0, v[130:131]
	s_mov_b32 m0, s12
	ds_read_b128 v[194:197], v158 offset:16384
	ds_read_b128 v[198:201], v158 offset:17408
	ds_read_b128 v[202:205], v158 offset:18432
	ds_read_b128 v[206:209], v158 offset:19456
	ds_read_b128 v[210:213], v158 offset:20480
	ds_read_b128 v[214:217], v158 offset:21504
	ds_read_b128 v[218:221], v158 offset:22528
	ds_read_b128 v[222:225], v158 offset:23552
	global_load_lds_dwordx4 v[152:153], off
	s_add_i32 m0, s12, 0x2000
	s_add_u32 s12, s58, 0x40000
	v_lshl_add_u64 v[226:227], s[58:59], 0, v[142:143]
	s_addc_u32 s13, s59, 0
	s_add_i32 s14, s15, s50
	global_load_lds_dwordx4 v[226:227], off
	v_lshl_add_u64 v[228:229], s[12:13], 0, v[130:131]
	s_mov_b32 m0, s14
	v_lshl_add_u64 v[230:231], s[66:67], 0, v[144:145]
	global_load_lds_dwordx4 v[228:229], off
	v_lshl_add_u64 v[228:229], s[12:13], 0, v[142:143]
	s_add_i32 m0, s14, 0x2000
	s_nop 0
	global_load_lds_dwordx4 v[228:229], off
	v_lshl_add_u64 v[228:229], s[66:67], 0, v[146:147]
	s_mov_b32 m0, s11
	s_nop 0
	global_load_lds_dwordx4 v[228:229], off
	s_mov_b32 m0, s30
	s_nop 0
	global_load_lds_dwordx4 v[230:231], off
	s_waitcnt vmcnt(8)
	s_waitcnt lgkmcnt(0)
	s_barrier
; #define PG8_STAGE(bufoff, gbase, voff) do { _Pragma("unroll") for (int _i = 0; _i < 2; ++_i) \
;         __builtin_amdgcn_global_load_lds((const unsigned*)((const char*)(gbase) + (voff)[_i]), (PG8_LAS unsigned*)(lds + (bufoff) + ldsw + _i * 8192), 16, 0, 0); } while (0)
; #define PG8_LDA(dst, b, h) do { _Pragma("unroll") for (int m = 0; m < 4; ++m) _Pragma("unroll") for (int k = 0; k < 2; ++k) dst[m][k] = *(const PG8_LAS bf16x8*)(lds + PG8_SA(b, h) + aoff + m * 2048 + k * 1024); } while (0)
; #define PG8_LDB(dst, b, h) do { _Pragma("unroll") for (int n = 0; n < 2; ++n) _Pragma("unroll") for (int k = 0; k < 2; ++k) dst[n][k] = *(const PG8_LAS bf16x8*)(lds + PG8_SB(b, h) + boff + n * 2048 + k * 1024); } while (0)
; #define PG8_MMA(ai, bj, At, Bt) do { __builtin_amdgcn_s_setprio(1); _Pragma("unroll") for (int m = 0; m < 4; ++m) _Pragma("unroll") for (int n = 0; n < 2; ++n) _Pragma("unroll") for (int k = 0; k < 2; ++k) \
;         acc[ai][bj][m][n] = __builtin_amdgcn_mfma_f32_16x16x32_bf16(Bt[n][k], At[m][k], acc[ai][bj][m][n], 0, 0, 0); __builtin_amdgcn_s_setprio(0); } while (0)
; #define PG8_WAIT_V(n) asm volatile("s_waitcnt vmcnt(" #n ")" ::: "memory")
; #define PG8_WAIT_L(n) asm volatile("s_waitcnt lgkmcnt(" #n ")" ::: "memory")
; #define PG8_BAR __builtin_amdgcn_s_barrier()
; #define PG8_SCHED __builtin_amdgcn_sched_barrier(0)
; template <class Epi, class Sched, bool ALIGN_EPI = false, bool SP2 = false>
; __device__ __forceinline__ void gemm_phase(PG8_LAS unsigned char* lds, const Gemm g, const Sched& S, const Epi& E) {
;     ...
;             PG8_WAIT_V(8); PG8_WAIT_L(0); PG8_BAR; PG8_MMA(1, 0, At, B0); PG8_MMA(1, 1, At, B1); PG8_BAR; PG8_SCHED;
;             PG8_LDB(B0, 1, 0); PG8_LDB(B1, 1, 1); PG8_SCHED; PG8_LDA(At, 1, 0); PG8_STAGE(PG8_SA(0, 1), a2 + hstep, voffA);
;             PG8_WAIT_V(8); PG8_WAIT_L(0); PG8_BAR; PG8_MMA(0, 0, At, B0); PG8_MMA(0, 1, At, B1); PG8_BAR; PG8_SCHED;
	s_setprio 1
	s_waitcnt lgkmcnt(0)
	v_mfma_f32_16x16x32_bf16 v[62:65], v[162:165], v[194:197], v[62:65]
	v_mfma_f32_16x16x32_bf16 v[58:61], v[170:173], v[194:197], v[58:61]
	v_mfma_f32_16x16x32_bf16 v[50:53], v[162:165], v[202:205], v[50:53]
	v_mfma_f32_16x16x32_bf16 v[42:45], v[170:173], v[202:205], v[42:45]
	v_mfma_f32_16x16x32_bf16 v[34:37], v[162:165], v[210:213], v[34:37]
	v_mfma_f32_16x16x32_bf16 v[26:29], v[170:173], v[210:213], v[26:29]
	v_mfma_f32_16x16x32_bf16 v[18:21], v[162:165], v[218:221], v[18:21]
	v_mfma_f32_16x16x32_bf16 v[10:13], v[170:173], v[218:221], v[10:13]
	v_mfma_f32_16x16x32_bf16 v[62:65], v[166:169], v[198:201], v[62:65]
	v_mfma_f32_16x16x32_bf16 v[58:61], v[174:177], v[198:201], v[58:61]
	v_mfma_f32_16x16x32_bf16 v[50:53], v[166:169], v[206:209], v[50:53]
	v_mfma_f32_16x16x32_bf16 v[42:45], v[174:177], v[206:209], v[42:45]
	v_mfma_f32_16x16x32_bf16 v[34:37], v[166:169], v[214:217], v[34:37]
	v_mfma_f32_16x16x32_bf16 v[26:29], v[174:177], v[214:217], v[26:29]
	v_mfma_f32_16x16x32_bf16 v[18:21], v[166:169], v[222:225], v[18:21]
	v_mfma_f32_16x16x32_bf16 v[10:13], v[174:177], v[222:225], v[10:13]
	v_mfma_f32_16x16x32_bf16 v[54:57], v[178:181], v[194:197], v[54:57]
	v_mfma_f32_16x16x32_bf16 v[46:49], v[186:189], v[194:197], v[46:49]
	v_mfma_f32_16x16x32_bf16 v[38:41], v[178:181], v[202:205], v[38:41]
	v_mfma_f32_16x16x32_bf16 v[30:33], v[186:189], v[202:205], v[30:33]
	v_mfma_f32_16x16x32_bf16 v[22:25], v[178:181], v[210:213], v[22:25]
	v_mfma_f32_16x16x32_bf16 v[14:17], v[186:189], v[210:213], v[14:17]
	v_mfma_f32_16x16x32_bf16 v[6:9], v[178:181], v[218:221], v[6:9]
	v_mfma_f32_16x16x32_bf16 v[2:5], v[186:189], v[218:221], v[2:5]
	v_mfma_f32_16x16x32_bf16 v[54:57], v[182:185], v[198:201], v[54:57]
	v_mfma_f32_16x16x32_bf16 v[46:49], v[190:193], v[198:201], v[46:49]
	v_mfma_f32_16x16x32_bf16 v[38:41], v[182:185], v[206:209], v[38:41]
	v_mfma_f32_16x16x32_bf16 v[30:33], v[190:193], v[206:209], v[30:33]
	v_mfma_f32_16x16x32_bf16 v[22:25], v[182:185], v[214:217], v[22:25]
	v_mfma_f32_16x16x32_bf16 v[14:17], v[190:193], v[214:217], v[14:17]
	v_mfma_f32_16x16x32_bf16 v[6:9], v[182:185], v[222:225], v[6:9]
	v_mfma_f32_16x16x32_bf16 v[2:5], v[190:193], v[222:225], v[2:5]
	s_setprio 0
	s_barrier
	s_add_i32 s14, 0, 0x18000
	v_add_u32_e32 v161, s14, v133
	s_add_i32 s15, 0, 0x1c000
	ds_read_b128 v[162:165], v161
	ds_read_b128 v[166:169], v161 offset:1024
	ds_read_b128 v[170:173], v161 offset:2048
	ds_read_b128 v[174:177], v161 offset:3072
	v_add_u32_e32 v161, s15, v133
	ds_read_b128 v[178:181], v161
	ds_read_b128 v[182:185], v161 offset:1024
	ds_read_b128 v[186:189], v161 offset:2048
	ds_read_b128 v[190:193], v161 offset:3072
	s_add_u32 s12, s66, 0x40000
	s_addc_u32 s13, s67, 0
	s_mov_b32 m0, s31
	v_lshl_add_u64 v[232:233], s[12:13], 0, v[146:147]
	ds_read_b128 v[194:197], v158 offset:32768
	ds_read_b128 v[198:201], v158 offset:33792
	ds_read_b128 v[202:205], v158 offset:34816
	ds_read_b128 v[206:209], v158 offset:35840
	ds_read_b128 v[210:213], v158 offset:36864
	ds_read_b128 v[214:217], v158 offset:37888
	ds_read_b128 v[218:221], v158 offset:38912
	ds_read_b128 v[222:225], v158 offset:39936
	global_load_lds_dwordx4 v[232:233], off
	v_lshl_add_u64 v[232:233], s[12:13], 0, v[144:145]
	s_mov_b32 m0, s86
	s_nop 0
	global_load_lds_dwordx4 v[232:233], off
	s_waitcnt vmcnt(8)
	s_waitcnt lgkmcnt(0)
	s_barrier
	s_setprio 1
	s_waitcnt lgkmcnt(0)
	v_mfma_f32_16x16x32_bf16 v[126:129], v[162:165], v[194:197], v[126:129]
	v_mfma_f32_16x16x32_bf16 v[122:125], v[170:173], v[194:197], v[122:125]
	v_mfma_f32_16x16x32_bf16 v[114:117], v[162:165], v[202:205], v[114:117]
	v_mfma_f32_16x16x32_bf16 v[106:109], v[170:173], v[202:205], v[106:109]
	v_mfma_f32_16x16x32_bf16 v[98:101], v[162:165], v[210:213], v[98:101]
	v_mfma_f32_16x16x32_bf16 v[90:93], v[170:173], v[210:213], v[90:93]
	v_mfma_f32_16x16x32_bf16 v[82:85], v[162:165], v[218:221], v[82:85]
	v_mfma_f32_16x16x32_bf16 v[74:77], v[170:173], v[218:221], v[74:77]
	v_mfma_f32_16x16x32_bf16 v[126:129], v[166:169], v[198:201], v[126:129]
	v_mfma_f32_16x16x32_bf16 v[122:125], v[174:177], v[198:201], v[122:125]
	v_mfma_f32_16x16x32_bf16 v[114:117], v[166:169], v[206:209], v[114:117]
	v_mfma_f32_16x16x32_bf16 v[106:109], v[174:177], v[206:209], v[106:109]
	v_mfma_f32_16x16x32_bf16 v[98:101], v[166:169], v[214:217], v[98:101]
	v_mfma_f32_16x16x32_bf16 v[90:93], v[174:177], v[214:217], v[90:93]
	v_mfma_f32_16x16x32_bf16 v[82:85], v[166:169], v[222:225], v[82:85]
	v_mfma_f32_16x16x32_bf16 v[74:77], v[174:177], v[222:225], v[74:77]
	v_mfma_f32_16x16x32_bf16 v[118:121], v[178:181], v[194:197], v[118:121]
	v_mfma_f32_16x16x32_bf16 v[110:113], v[186:189], v[194:197], v[110:113]
	v_mfma_f32_16x16x32_bf16 v[102:105], v[178:181], v[202:205], v[102:105]
	v_mfma_f32_16x16x32_bf16 v[94:97], v[186:189], v[202:205], v[94:97]
	v_mfma_f32_16x16x32_bf16 v[86:89], v[178:181], v[210:213], v[86:89]
	v_mfma_f32_16x16x32_bf16 v[78:81], v[186:189], v[210:213], v[78:81]
	v_mfma_f32_16x16x32_bf16 v[70:73], v[178:181], v[218:221], v[70:73]
	v_mfma_f32_16x16x32_bf16 v[66:69], v[186:189], v[218:221], v[66:69]
	v_mfma_f32_16x16x32_bf16 v[118:121], v[182:185], v[198:201], v[118:121]
	v_mfma_f32_16x16x32_bf16 v[110:113], v[190:193], v[198:201], v[110:113]
	v_mfma_f32_16x16x32_bf16 v[102:105], v[182:185], v[206:209], v[102:105]
	v_mfma_f32_16x16x32_bf16 v[94:97], v[190:193], v[206:209], v[94:97]
	v_mfma_f32_16x16x32_bf16 v[86:89], v[182:185], v[214:217], v[86:89]
	v_mfma_f32_16x16x32_bf16 v[78:81], v[190:193], v[214:217], v[78:81]
	v_mfma_f32_16x16x32_bf16 v[70:73], v[182:185], v[222:225], v[70:73]
	v_mfma_f32_16x16x32_bf16 v[66:69], v[190:193], v[222:225], v[66:69]
	s_setprio 0
	s_barrier
; #define PG8_STAGE(bufoff, gbase, voff) do { _Pragma("unroll") for (int _i = 0; _i < 2; ++_i) \
;         __builtin_amdgcn_global_load_lds((const unsigned*)((const char*)(gbase) + (voff)[_i]), (PG8_LAS unsigned*)(lds + (bufoff) + ldsw + _i * 8192), 16, 0, 0); } while (0)
; #define PG8_LDA(dst, b, h) do { _Pragma("unroll") for (int m = 0; m < 4; ++m) _Pragma("unroll") for (int k = 0; k < 2; ++k) dst[m][k] = *(const PG8_LAS bf16x8*)(lds + PG8_SA(b, h) + aoff + m * 2048 + k * 1024); } while (0)
; #define PG8_MMA(ai, bj, At, Bt) do { __builtin_amdgcn_s_setprio(1); _Pragma("unroll") for (int m = 0; m < 4; ++m) _Pragma("unroll") for (int n = 0; n < 2; ++n) _Pragma("unroll") for (int k = 0; k < 2; ++k) \
;         acc[ai][bj][m][n] = __builtin_amdgcn_mfma_f32_16x16x32_bf16(Bt[n][k], At[m][k], acc[ai][bj][m][n], 0, 0, 0); __builtin_amdgcn_s_setprio(0); } while (0)
; #define PG8_WAIT_V(n) asm volatile("s_waitcnt vmcnt(" #n ")" ::: "memory")
; #define PG8_WAIT_L(n) asm volatile("s_waitcnt lgkmcnt(" #n ")" ::: "memory")
; #define PG8_BAR __builtin_amdgcn_s_barrier()
; #define PG8_SCHED __builtin_amdgcn_sched_barrier(0)
; template <class Epi, class Sched, bool ALIGN_EPI = false, bool SP2 = false>
; __device__ __forceinline__ void gemm_phase(PG8_LAS unsigned char* lds, const Gemm g, const Sched& S, const Epi& E) {
;     ...
;             PG8_LDA(At, 1, 1); PG8_STAGE(PG8_SB(1, 0), b3, voffB); PG8_STAGE(PG8_SB(1, 1), b3 + hstep, voffB); PG8_STAGE(PG8_SA(1, 0), a3, voffA);
;             PG8_WAIT_V(8); PG8_WAIT_L(0); PG8_BAR; PG8_MMA(1, 0, At, B0); PG8_MMA(1, 1, At, B1); PG8_BAR; PG8_SCHED;
;     ...
;         if constexpr (ALIGN_EPI) { if (wr == 0) PG8_BAR; }
	s_add_i32 s12, s14, s50
	v_lshl_add_u64 v[152:153], v[152:153], 0, s[46:47]
	s_mov_b32 m0, s12
	ds_read_b128 v[194:197], v158 offset:49152
	ds_read_b128 v[198:201], v158 offset:50176
	ds_read_b128 v[202:205], v158 offset:51200
	ds_read_b128 v[206:209], v158 offset:52224
	ds_read_b128 v[210:213], v158 offset:53248
	ds_read_b128 v[214:217], v158 offset:54272
	ds_read_b128 v[218:221], v158 offset:55296
	ds_read_b128 v[222:225], v158 offset:56320
	global_load_lds_dwordx4 v[152:153], off
	s_add_i32 m0, s12, 0x2000
	s_add_u32 s12, s58, 0x40080
	v_lshl_add_u64 v[152:153], v[226:227], 0, s[46:47]
	s_addc_u32 s13, s59, 0
	s_add_i32 s14, s15, s50
	global_load_lds_dwordx4 v[152:153], off
	v_lshl_add_u64 v[152:153], s[12:13], 0, v[130:131]
	s_mov_b32 m0, s14
	s_nop 0
	global_load_lds_dwordx4 v[152:153], off
	v_lshl_add_u64 v[152:153], s[12:13], 0, v[142:143]
	s_add_i32 m0, s14, 0x2000
	s_nop 0
	global_load_lds_dwordx4 v[152:153], off
	v_lshl_add_u64 v[152:153], v[228:229], 0, s[46:47]
	s_mov_b32 m0, s38
	s_nop 0
	global_load_lds_dwordx4 v[152:153], off
	v_lshl_add_u64 v[152:153], v[230:231], 0, s[46:47]
	s_mov_b32 m0, s39
	s_nop 0
	global_load_lds_dwordx4 v[152:153], off
	s_waitcnt vmcnt(8)
	s_waitcnt lgkmcnt(0)
	s_barrier
	s_setprio 1
	s_waitcnt lgkmcnt(0)
	v_mfma_f32_16x16x32_bf16 v[62:65], v[162:165], v[194:197], v[62:65]
	v_mfma_f32_16x16x32_bf16 v[58:61], v[170:173], v[194:197], v[58:61]
	v_mfma_f32_16x16x32_bf16 v[50:53], v[162:165], v[202:205], v[50:53]
	v_mfma_f32_16x16x32_bf16 v[42:45], v[170:173], v[202:205], v[42:45]
	v_mfma_f32_16x16x32_bf16 v[34:37], v[162:165], v[210:213], v[34:37]
	v_mfma_f32_16x16x32_bf16 v[26:29], v[170:173], v[210:213], v[26:29]
	v_mfma_f32_16x16x32_bf16 v[18:21], v[162:165], v[218:221], v[18:21]
	v_mfma_f32_16x16x32_bf16 v[10:13], v[170:173], v[218:221], v[10:13]
	v_mfma_f32_16x16x32_bf16 v[62:65], v[166:169], v[198:201], v[62:65]
	v_mfma_f32_16x16x32_bf16 v[58:61], v[174:177], v[198:201], v[58:61]
	v_mfma_f32_16x16x32_bf16 v[50:53], v[166:169], v[206:209], v[50:53]
	v_mfma_f32_16x16x32_bf16 v[42:45], v[174:177], v[206:209], v[42:45]
	v_mfma_f32_16x16x32_bf16 v[34:37], v[166:169], v[214:217], v[34:37]
	v_mfma_f32_16x16x32_bf16 v[26:29], v[174:177], v[214:217], v[26:29]
	v_mfma_f32_16x16x32_bf16 v[18:21], v[166:169], v[222:225], v[18:21]
	v_mfma_f32_16x16x32_bf16 v[10:13], v[174:177], v[222:225], v[10:13]
	v_mfma_f32_16x16x32_bf16 v[54:57], v[178:181], v[194:197], v[54:57]
	v_mfma_f32_16x16x32_bf16 v[46:49], v[186:189], v[194:197], v[46:49]
	v_mfma_f32_16x16x32_bf16 v[38:41], v[178:181], v[202:205], v[38:41]
	v_mfma_f32_16x16x32_bf16 v[30:33], v[186:189], v[202:205], v[30:33]
	v_mfma_f32_16x16x32_bf16 v[22:25], v[178:181], v[210:213], v[22:25]
	v_mfma_f32_16x16x32_bf16 v[14:17], v[186:189], v[210:213], v[14:17]
	v_mfma_f32_16x16x32_bf16 v[6:9], v[178:181], v[218:221], v[6:9]
	v_mfma_f32_16x16x32_bf16 v[2:5], v[186:189], v[218:221], v[2:5]
	v_mfma_f32_16x16x32_bf16 v[54:57], v[182:185], v[198:201], v[54:57]
	v_mfma_f32_16x16x32_bf16 v[46:49], v[190:193], v[198:201], v[46:49]
	v_mfma_f32_16x16x32_bf16 v[38:41], v[182:185], v[206:209], v[38:41]
	v_mfma_f32_16x16x32_bf16 v[30:33], v[190:193], v[206:209], v[30:33]
	v_mfma_f32_16x16x32_bf16 v[22:25], v[182:185], v[214:217], v[22:25]
	v_mfma_f32_16x16x32_bf16 v[14:17], v[190:193], v[214:217], v[14:17]
	v_mfma_f32_16x16x32_bf16 v[6:9], v[182:185], v[222:225], v[6:9]
	v_mfma_f32_16x16x32_bf16 v[2:5], v[190:193], v[222:225], v[2:5]
	s_setprio 0
	s_barrier
	s_add_i32 s10, s10, 2
	s_add_u32 s56, s56, 0x100
	s_addc_u32 s57, s57, 0
	s_add_u32 vcc_hi, vcc_hi, 0x100
	s_addc_u32 s2, s2, 0
	s_cmp_gt_u32 s10, 13
	s_cbranch_scc0 .LBB0_252
	s_and_b64 vcc, exec, s[48:49]
	s_cbranch_vccz .LBB0_255
	s_barrier

; #define PG8_STAGE(bufoff, gbase, voff) do { _Pragma("unroll") for (int _i = 0; _i < 2; ++_i) \
;         __builtin_amdgcn_global_load_lds((const unsigned*)((const char*)(gbase) + (voff)[_i]), (PG8_LAS unsigned*)(lds + (bufoff) + ldsw + _i * 8192), 16, 0, 0); } while (0)
; #define PG8_LDA(dst, b, h) do { _Pragma("unroll") for (int m = 0; m < 4; ++m) _Pragma("unroll") for (int k = 0; k < 2; ++k) dst[m][k] = *(const PG8_LAS bf16x8*)(lds + PG8_SA(b, h) + aoff + m * 2048 + k * 1024); } while (0)
; #define PG8_LDB(dst, b, h) do { _Pragma("unroll") for (int n = 0; n < 2; ++n) _Pragma("unroll") for (int k = 0; k < 2; ++k) dst[n][k] = *(const PG8_LAS bf16x8*)(lds + PG8_SB(b, h) + boff + n * 2048 + k * 1024); } while (0)
; #define PG8_MMA(ai, bj, At, Bt) do { __builtin_amdgcn_s_setprio(1); _Pragma("unroll") for (int m = 0; m < 4; ++m) _Pragma("unroll") for (int n = 0; n < 2; ++n) _Pragma("unroll") for (int k = 0; k < 2; ++k) \
;         acc[ai][bj][m][n] = __builtin_amdgcn_mfma_f32_16x16x32_bf16(Bt[n][k], At[m][k], acc[ai][bj][m][n], 0, 0, 0); __builtin_amdgcn_s_setprio(0); } while (0)
; #define PG8_WAIT_V(n) asm volatile("s_waitcnt vmcnt(" #n ")" ::: "memory")
; #define PG8_WAIT_L(n) asm volatile("s_waitcnt lgkmcnt(" #n ")" ::: "memory")
; #define PG8_BAR __builtin_amdgcn_s_barrier()
; #define PG8_SCHED __builtin_amdgcn_sched_barrier(0)
; template <class Epi, class Sched, bool ALIGN_EPI = false, bool SP2 = false>
; __device__ __forceinline__ void gemm_phase(PG8_LAS unsigned char* lds, const Gemm g, const Sched& S, const Epi& E) {
;     ...
;             PG8_LDB(B0, 0, 0); PG8_LDB(B1, 0, 1); PG8_SCHED; PG8_LDA(At, 0, 0); PG8_STAGE(PG8_SA(1, 1), a1 + hstep, voffA);
;             PG8_WAIT_V(8); PG8_WAIT_L(0); PG8_BAR; PG8_MMA(0, 0, At, B0); PG8_MMA(0, 1, At, B1); PG8_BAR; PG8_SCHED;
;             PG8_LDA(At, 0, 1); PG8_STAGE(PG8_SB(0, 0), b2, voffB); PG8_STAGE(PG8_SB(0, 1), b2 + hstep, voffB); PG8_STAGE(PG8_SA(0, 0), a2, voffA);
.LBB0_833:
	s_add_u32 s34, s56, 0xfffc0080
	s_addc_u32 s35, s57, -1
	s_add_i32 s76, 0, 0x10000
	s_cmp_eq_u32 s81, 12
	s_cselect_b32 s67, s50, s35
	s_cselect_b32 s66, s61, s34
	s_cselect_b32 s65, s59, s78
	s_cselect_b32 s64, s75, s77
	s_add_i32 s34, 0, 0x14000
	v_add_u32_e32 v142, s76, v232
	v_add_u32_e32 v158, s34, v232
	ds_read_b128 v[130:133], v142
	ds_read_b128 v[134:137], v142 offset:1024
	ds_read_b128 v[138:141], v142 offset:2048
	ds_read_b128 v[142:145], v142 offset:3072
	ds_read_b128 v[146:149], v158
	ds_read_b128 v[150:153], v158 offset:1024
	ds_read_b128 v[154:157], v158 offset:2048
	ds_read_b128 v[158:161], v158 offset:3072
	v_lshl_add_u64 v[212:213], s[56:57], 0, v[200:201]
	s_add_i32 m0, s22, 0xc000
	ds_read_b128 v[162:165], v235
	ds_read_b128 v[166:169], v235 offset:1024
	ds_read_b128 v[170:173], v235 offset:2048
	ds_read_b128 v[174:177], v235 offset:3072
	ds_read_b128 v[178:181], v235 offset:4096
	ds_read_b128 v[182:185], v235 offset:5120
	ds_read_b128 v[204:207], v235 offset:6144
	ds_read_b128 v[208:211], v235 offset:7168
	global_load_lds_dwordx4 v[212:213], off
	v_lshl_add_u64 v[212:213], s[56:57], 0, v[202:203]
	s_add_i32 m0, s22, 0xe000
	s_nop 0
	global_load_lds_dwordx4 v[212:213], off
	s_waitcnt vmcnt(8)
	s_waitcnt lgkmcnt(0)
	s_barrier
	s_setprio 1
	s_waitcnt lgkmcnt(0)
	v_mfma_f32_16x16x32_bf16 v[126:129], v[130:133], v[162:165], v[126:129]
	v_mfma_f32_16x16x32_bf16 v[122:125], v[138:141], v[162:165], v[122:125]
	v_mfma_f32_16x16x32_bf16 v[110:113], v[130:133], v[170:173], v[110:113]
	v_mfma_f32_16x16x32_bf16 v[106:109], v[138:141], v[170:173], v[106:109]
	v_mfma_f32_16x16x32_bf16 v[94:97], v[130:133], v[178:181], v[94:97]
	v_mfma_f32_16x16x32_bf16 v[90:93], v[138:141], v[178:181], v[90:93]
	v_mfma_f32_16x16x32_bf16 v[78:81], v[130:133], v[204:207], v[78:81]
	v_mfma_f32_16x16x32_bf16 v[74:77], v[138:141], v[204:207], v[74:77]
	v_mfma_f32_16x16x32_bf16 v[126:129], v[134:137], v[166:169], v[126:129]
	v_mfma_f32_16x16x32_bf16 v[122:125], v[142:145], v[166:169], v[122:125]
	v_mfma_f32_16x16x32_bf16 v[110:113], v[134:137], v[174:177], v[110:113]
	v_mfma_f32_16x16x32_bf16 v[106:109], v[142:145], v[174:177], v[106:109]
	v_mfma_f32_16x16x32_bf16 v[94:97], v[134:137], v[182:185], v[94:97]
	v_mfma_f32_16x16x32_bf16 v[90:93], v[142:145], v[182:185], v[90:93]
	v_mfma_f32_16x16x32_bf16 v[78:81], v[134:137], v[208:211], v[78:81]
	v_mfma_f32_16x16x32_bf16 v[74:77], v[142:145], v[208:211], v[74:77]
	v_mfma_f32_16x16x32_bf16 v[118:121], v[146:149], v[162:165], v[118:121]
	v_mfma_f32_16x16x32_bf16 v[114:117], v[154:157], v[162:165], v[114:117]
	v_mfma_f32_16x16x32_bf16 v[102:105], v[146:149], v[170:173], v[102:105]
	v_mfma_f32_16x16x32_bf16 v[98:101], v[154:157], v[170:173], v[98:101]
	v_mfma_f32_16x16x32_bf16 v[86:89], v[146:149], v[178:181], v[86:89]
	v_mfma_f32_16x16x32_bf16 v[82:85], v[154:157], v[178:181], v[82:85]
	v_mfma_f32_16x16x32_bf16 v[70:73], v[146:149], v[204:207], v[70:73]
	v_mfma_f32_16x16x32_bf16 v[66:69], v[154:157], v[204:207], v[66:69]
	v_mfma_f32_16x16x32_bf16 v[118:121], v[150:153], v[166:169], v[118:121]
	v_mfma_f32_16x16x32_bf16 v[114:117], v[158:161], v[166:169], v[114:117]
	v_mfma_f32_16x16x32_bf16 v[102:105], v[150:153], v[174:177], v[102:105]
	v_mfma_f32_16x16x32_bf16 v[98:101], v[158:161], v[174:177], v[98:101]
	v_mfma_f32_16x16x32_bf16 v[86:89], v[150:153], v[182:185], v[86:89]
	v_mfma_f32_16x16x32_bf16 v[82:85], v[158:161], v[182:185], v[82:85]
	v_mfma_f32_16x16x32_bf16 v[70:73], v[150:153], v[208:211], v[70:73]
	v_mfma_f32_16x16x32_bf16 v[66:69], v[158:161], v[208:211], v[66:69]
	s_setprio 0
	s_barrier
	s_add_i32 s35, s76, s2
	v_lshl_add_u64 v[212:213], s[64:65], 0, v[198:199]
	s_mov_b32 m0, s35
	ds_read_b128 v[162:165], v235 offset:16384
	ds_read_b128 v[166:169], v235 offset:17408
	ds_read_b128 v[170:173], v235 offset:18432
	ds_read_b128 v[174:177], v235 offset:19456
	ds_read_b128 v[178:181], v235 offset:20480
	ds_read_b128 v[182:185], v235 offset:21504
	ds_read_b128 v[204:207], v235 offset:22528
	ds_read_b128 v[208:211], v235 offset:23552
	global_load_lds_dwordx4 v[212:213], off
	s_add_i32 m0, s35, 0x2000
	s_add_u32 s82, s64, 0x40000
	v_lshl_add_u64 v[214:215], s[64:65], 0, v[194:195]
	s_addc_u32 s83, s65, 0
	s_add_i32 s34, s34, s2
	global_load_lds_dwordx4 v[214:215], off
	v_lshl_add_u64 v[216:217], s[82:83], 0, v[198:199]
	s_mov_b32 m0, s34
	v_lshl_add_u64 v[218:219], s[66:67], 0, v[196:197]
	global_load_lds_dwordx4 v[216:217], off
	v_lshl_add_u64 v[216:217], s[82:83], 0, v[194:195]
	s_add_i32 m0, s34, 0x2000
	s_nop 0
	global_load_lds_dwordx4 v[216:217], off
	v_lshl_add_u64 v[216:217], s[66:67], 0, v[186:187]
	s_mov_b32 m0, s22
	s_nop 0
	global_load_lds_dwordx4 v[216:217], off
	s_mov_b32 m0, s23
	s_nop 0
	global_load_lds_dwordx4 v[218:219], off
	s_waitcnt vmcnt(8)
	s_waitcnt lgkmcnt(0)
	s_barrier
; #define PG8_STAGE(bufoff, gbase, voff) do { _Pragma("unroll") for (int _i = 0; _i < 2; ++_i) \
;         __builtin_amdgcn_global_load_lds((const unsigned*)((const char*)(gbase) + (voff)[_i]), (PG8_LAS unsigned*)(lds + (bufoff) + ldsw + _i * 8192), 16, 0, 0); } while (0)
; #define PG8_LDA(dst, b, h) do { _Pragma("unroll") for (int m = 0; m < 4; ++m) _Pragma("unroll") for (int k = 0; k < 2; ++k) dst[m][k] = *(const PG8_LAS bf16x8*)(lds + PG8_SA(b, h) + aoff + m * 2048 + k * 1024); } while (0)
; #define PG8_LDB(dst, b, h) do { _Pragma("unroll") for (int n = 0; n < 2; ++n) _Pragma("unroll") for (int k = 0; k < 2; ++k) dst[n][k] = *(const PG8_LAS bf16x8*)(lds + PG8_SB(b, h) + boff + n * 2048 + k * 1024); } while (0)
; #define PG8_MMA(ai, bj, At, Bt) do { __builtin_amdgcn_s_setprio(1); _Pragma("unroll") for (int m = 0; m < 4; ++m) _Pragma("unroll") for (int n = 0; n < 2; ++n) _Pragma("unroll") for (int k = 0; k < 2; ++k) \
;         acc[ai][bj][m][n] = __builtin_amdgcn_mfma_f32_16x16x32_bf16(Bt[n][k], At[m][k], acc[ai][bj][m][n], 0, 0, 0); __builtin_amdgcn_s_setprio(0); } while (0)
; #define PG8_WAIT_V(n) asm volatile("s_waitcnt vmcnt(" #n ")" ::: "memory")
; #define PG8_WAIT_L(n) asm volatile("s_waitcnt lgkmcnt(" #n ")" ::: "memory")
; #define PG8_BAR __builtin_amdgcn_s_barrier()
; #define PG8_SCHED __builtin_amdgcn_sched_barrier(0)
; template <class Epi, class Sched, bool ALIGN_EPI = false, bool SP2 = false>
; __device__ __forceinline__ void gemm_phase(PG8_LAS unsigned char* lds, const Gemm g, const Sched& S, const Epi& E) {
;     ...
;             PG8_WAIT_V(8); PG8_WAIT_L(0); PG8_BAR; PG8_MMA(1, 0, At, B0); PG8_MMA(1, 1, At, B1); PG8_BAR; PG8_SCHED;
;             PG8_LDB(B0, 1, 0); PG8_LDB(B1, 1, 1); PG8_SCHED; PG8_LDA(At, 1, 0); PG8_STAGE(PG8_SA(0, 1), a2 + hstep, voffA);
;             PG8_WAIT_V(8); PG8_WAIT_L(0); PG8_BAR; PG8_MMA(0, 0, At, B0); PG8_MMA(0, 1, At, B1); PG8_BAR; PG8_SCHED;
	s_setprio 1
	s_waitcnt lgkmcnt(0)
	v_mfma_f32_16x16x32_bf16 v[62:65], v[130:133], v[162:165], v[62:65]
	v_mfma_f32_16x16x32_bf16 v[58:61], v[138:141], v[162:165], v[58:61]
	v_mfma_f32_16x16x32_bf16 v[46:49], v[130:133], v[170:173], v[46:49]
	v_mfma_f32_16x16x32_bf16 v[42:45], v[138:141], v[170:173], v[42:45]
	v_mfma_f32_16x16x32_bf16 v[30:33], v[130:133], v[178:181], v[30:33]
	v_mfma_f32_16x16x32_bf16 v[26:29], v[138:141], v[178:181], v[26:29]
	v_mfma_f32_16x16x32_bf16 v[14:17], v[130:133], v[204:207], v[14:17]
	v_mfma_f32_16x16x32_bf16 v[10:13], v[138:141], v[204:207], v[10:13]
	v_mfma_f32_16x16x32_bf16 v[62:65], v[134:137], v[166:169], v[62:65]
	v_mfma_f32_16x16x32_bf16 v[58:61], v[142:145], v[166:169], v[58:61]
	v_mfma_f32_16x16x32_bf16 v[46:49], v[134:137], v[174:177], v[46:49]
	v_mfma_f32_16x16x32_bf16 v[42:45], v[142:145], v[174:177], v[42:45]
	v_mfma_f32_16x16x32_bf16 v[30:33], v[134:137], v[182:185], v[30:33]
	v_mfma_f32_16x16x32_bf16 v[26:29], v[142:145], v[182:185], v[26:29]
	v_mfma_f32_16x16x32_bf16 v[14:17], v[134:137], v[208:211], v[14:17]
	v_mfma_f32_16x16x32_bf16 v[10:13], v[142:145], v[208:211], v[10:13]
	v_mfma_f32_16x16x32_bf16 v[54:57], v[146:149], v[162:165], v[54:57]
	v_mfma_f32_16x16x32_bf16 v[50:53], v[154:157], v[162:165], v[50:53]
	v_mfma_f32_16x16x32_bf16 v[38:41], v[146:149], v[170:173], v[38:41]
	v_mfma_f32_16x16x32_bf16 v[34:37], v[154:157], v[170:173], v[34:37]
	v_mfma_f32_16x16x32_bf16 v[22:25], v[146:149], v[178:181], v[22:25]
	v_mfma_f32_16x16x32_bf16 v[18:21], v[154:157], v[178:181], v[18:21]
	v_mfma_f32_16x16x32_bf16 v[6:9], v[146:149], v[204:207], v[6:9]
	v_mfma_f32_16x16x32_bf16 v[2:5], v[154:157], v[204:207], v[2:5]
	v_mfma_f32_16x16x32_bf16 v[54:57], v[150:153], v[166:169], v[54:57]
	v_mfma_f32_16x16x32_bf16 v[50:53], v[158:161], v[166:169], v[50:53]
	v_mfma_f32_16x16x32_bf16 v[38:41], v[150:153], v[174:177], v[38:41]
	v_mfma_f32_16x16x32_bf16 v[34:37], v[158:161], v[174:177], v[34:37]
	v_mfma_f32_16x16x32_bf16 v[22:25], v[150:153], v[182:185], v[22:25]
	v_mfma_f32_16x16x32_bf16 v[18:21], v[158:161], v[182:185], v[18:21]
	v_mfma_f32_16x16x32_bf16 v[6:9], v[150:153], v[208:211], v[6:9]
	v_mfma_f32_16x16x32_bf16 v[2:5], v[158:161], v[208:211], v[2:5]
	s_setprio 0
	s_barrier
	s_add_i32 s34, 0, 0x18000
	s_add_i32 s35, 0, 0x1c000
	v_add_u32_e32 v142, s34, v232
	v_add_u32_e32 v158, s35, v232
	ds_read_b128 v[130:133], v142
	ds_read_b128 v[134:137], v142 offset:1024
	ds_read_b128 v[138:141], v142 offset:2048
	ds_read_b128 v[142:145], v142 offset:3072
	ds_read_b128 v[146:149], v158
	ds_read_b128 v[150:153], v158 offset:1024
	ds_read_b128 v[154:157], v158 offset:2048
	ds_read_b128 v[158:161], v158 offset:3072
	s_add_u32 s66, s66, 0x40000
	s_addc_u32 s67, s67, 0
	s_mov_b32 m0, s47
	v_lshl_add_u64 v[220:221], s[66:67], 0, v[186:187]
	ds_read_b128 v[162:165], v235 offset:32768
	ds_read_b128 v[166:169], v235 offset:33792
	ds_read_b128 v[170:173], v235 offset:34816
	ds_read_b128 v[174:177], v235 offset:35840
	ds_read_b128 v[178:181], v235 offset:36864
	ds_read_b128 v[182:185], v235 offset:37888
	ds_read_b128 v[204:207], v235 offset:38912
	ds_read_b128 v[208:211], v235 offset:39936
	global_load_lds_dwordx4 v[220:221], off
	v_lshl_add_u64 v[220:221], s[66:67], 0, v[196:197]
	s_mov_b32 m0, s51
	s_nop 0
	global_load_lds_dwordx4 v[220:221], off
	s_waitcnt vmcnt(8)
	s_waitcnt lgkmcnt(0)
	s_barrier
	s_setprio 1
	s_waitcnt lgkmcnt(0)
	v_mfma_f32_16x16x32_bf16 v[126:129], v[130:133], v[162:165], v[126:129]
	v_mfma_f32_16x16x32_bf16 v[122:125], v[138:141], v[162:165], v[122:125]
	v_mfma_f32_16x16x32_bf16 v[110:113], v[130:133], v[170:173], v[110:113]
	v_mfma_f32_16x16x32_bf16 v[106:109], v[138:141], v[170:173], v[106:109]
	v_mfma_f32_16x16x32_bf16 v[94:97], v[130:133], v[178:181], v[94:97]
	v_mfma_f32_16x16x32_bf16 v[90:93], v[138:141], v[178:181], v[90:93]
	v_mfma_f32_16x16x32_bf16 v[78:81], v[130:133], v[204:207], v[78:81]
	v_mfma_f32_16x16x32_bf16 v[74:77], v[138:141], v[204:207], v[74:77]
	v_mfma_f32_16x16x32_bf16 v[126:129], v[134:137], v[166:169], v[126:129]
	v_mfma_f32_16x16x32_bf16 v[122:125], v[142:145], v[166:169], v[122:125]
	v_mfma_f32_16x16x32_bf16 v[110:113], v[134:137], v[174:177], v[110:113]
	v_mfma_f32_16x16x32_bf16 v[106:109], v[142:145], v[174:177], v[106:109]
	v_mfma_f32_16x16x32_bf16 v[94:97], v[134:137], v[182:185], v[94:97]
	v_mfma_f32_16x16x32_bf16 v[90:93], v[142:145], v[182:185], v[90:93]
	v_mfma_f32_16x16x32_bf16 v[78:81], v[134:137], v[208:211], v[78:81]
	v_mfma_f32_16x16x32_bf16 v[74:77], v[142:145], v[208:211], v[74:77]
	v_mfma_f32_16x16x32_bf16 v[118:121], v[146:149], v[162:165], v[118:121]
	v_mfma_f32_16x16x32_bf16 v[114:117], v[154:157], v[162:165], v[114:117]
	v_mfma_f32_16x16x32_bf16 v[102:105], v[146:149], v[170:173], v[102:105]
	v_mfma_f32_16x16x32_bf16 v[98:101], v[154:157], v[170:173], v[98:101]
	v_mfma_f32_16x16x32_bf16 v[86:89], v[146:149], v[178:181], v[86:89]
	v_mfma_f32_16x16x32_bf16 v[82:85], v[154:157], v[178:181], v[82:85]
	v_mfma_f32_16x16x32_bf16 v[70:73], v[146:149], v[204:207], v[70:73]
	v_mfma_f32_16x16x32_bf16 v[66:69], v[154:157], v[204:207], v[66:69]
	v_mfma_f32_16x16x32_bf16 v[118:121], v[150:153], v[166:169], v[118:121]
	v_mfma_f32_16x16x32_bf16 v[114:117], v[158:161], v[166:169], v[114:117]
	v_mfma_f32_16x16x32_bf16 v[102:105], v[150:153], v[174:177], v[102:105]
	v_mfma_f32_16x16x32_bf16 v[98:101], v[158:161], v[174:177], v[98:101]
	v_mfma_f32_16x16x32_bf16 v[86:89], v[150:153], v[182:185], v[86:89]
	v_mfma_f32_16x16x32_bf16 v[82:85], v[158:161], v[182:185], v[82:85]
	v_mfma_f32_16x16x32_bf16 v[70:73], v[150:153], v[208:211], v[70:73]
	v_mfma_f32_16x16x32_bf16 v[66:69], v[158:161], v[208:211], v[66:69]
	s_setprio 0
	s_barrier
; #define PG8_STAGE(bufoff, gbase, voff) do { _Pragma("unroll") for (int _i = 0; _i < 2; ++_i) \
;         __builtin_amdgcn_global_load_lds((const unsigned*)((const char*)(gbase) + (voff)[_i]), (PG8_LAS unsigned*)(lds + (bufoff) + ldsw + _i * 8192), 16, 0, 0); } while (0)
; #define PG8_LDA(dst, b, h) do { _Pragma("unroll") for (int m = 0; m < 4; ++m) _Pragma("unroll") for (int k = 0; k < 2; ++k) dst[m][k] = *(const PG8_LAS bf16x8*)(lds + PG8_SA(b, h) + aoff + m * 2048 + k * 1024); } while (0)
; #define PG8_MMA(ai, bj, At, Bt) do { __builtin_amdgcn_s_setprio(1); _Pragma("unroll") for (int m = 0; m < 4; ++m) _Pragma("unroll") for (int n = 0; n < 2; ++n) _Pragma("unroll") for (int k = 0; k < 2; ++k) \
;         acc[ai][bj][m][n] = __builtin_amdgcn_mfma_f32_16x16x32_bf16(Bt[n][k], At[m][k], acc[ai][bj][m][n], 0, 0, 0); __builtin_amdgcn_s_setprio(0); } while (0)
; #define PG8_WAIT_V(n) asm volatile("s_waitcnt vmcnt(" #n ")" ::: "memory")
; #define PG8_WAIT_L(n) asm volatile("s_waitcnt lgkmcnt(" #n ")" ::: "memory")
; #define PG8_BAR __builtin_amdgcn_s_barrier()
; #define PG8_SCHED __builtin_amdgcn_sched_barrier(0)
; template <class Epi, class Sched, bool ALIGN_EPI = false, bool SP2 = false>
; __device__ __forceinline__ void gemm_phase(PG8_LAS unsigned char* lds, const Gemm g, const Sched& S, const Epi& E) {
;     ...
;             PG8_LDA(At, 1, 1); PG8_STAGE(PG8_SB(1, 0), b3, voffB); PG8_STAGE(PG8_SB(1, 1), b3 + hstep, voffB); PG8_STAGE(PG8_SA(1, 0), a3, voffA);
;             PG8_WAIT_V(8); PG8_WAIT_L(0); PG8_BAR; PG8_MMA(1, 0, At, B0); PG8_MMA(1, 1, At, B1); PG8_BAR; PG8_SCHED;
;     ...
;         if constexpr (ALIGN_EPI) { if (wr == 0) PG8_BAR; }
	s_add_i32 s34, s34, s2
	v_lshl_add_u64 v[212:213], v[212:213], 0, s[44:45]
	s_mov_b32 m0, s34
	ds_read_b128 v[162:165], v235 offset:49152
	ds_read_b128 v[166:169], v235 offset:50176
	ds_read_b128 v[170:173], v235 offset:51200
	ds_read_b128 v[174:177], v235 offset:52224
	ds_read_b128 v[178:181], v235 offset:53248
	ds_read_b128 v[182:185], v235 offset:54272
	ds_read_b128 v[204:207], v235 offset:55296
	ds_read_b128 v[208:211], v235 offset:56320
	global_load_lds_dwordx4 v[212:213], off
	s_add_i32 m0, s34, 0x2000
	s_add_u32 s64, s64, 0x40080
	v_lshl_add_u64 v[212:213], v[214:215], 0, s[44:45]
	s_addc_u32 s65, s65, 0
	s_add_i32 s34, s35, s2
	global_load_lds_dwordx4 v[212:213], off
	v_lshl_add_u64 v[212:213], s[64:65], 0, v[198:199]
	s_mov_b32 m0, s34
	s_nop 0
	global_load_lds_dwordx4 v[212:213], off
	v_lshl_add_u64 v[212:213], s[64:65], 0, v[194:195]
	s_add_i32 m0, s34, 0x2000
	s_nop 0
	global_load_lds_dwordx4 v[212:213], off
	v_lshl_add_u64 v[212:213], v[216:217], 0, s[44:45]
	s_mov_b32 m0, s42
	s_nop 0
	global_load_lds_dwordx4 v[212:213], off
	v_lshl_add_u64 v[212:213], v[218:219], 0, s[44:45]
	s_mov_b32 m0, s43
	s_nop 0
	global_load_lds_dwordx4 v[212:213], off
	s_waitcnt vmcnt(8)
	s_waitcnt lgkmcnt(0)
	s_barrier
	s_setprio 1
	s_waitcnt lgkmcnt(0)
	v_mfma_f32_16x16x32_bf16 v[62:65], v[130:133], v[162:165], v[62:65]
	v_mfma_f32_16x16x32_bf16 v[58:61], v[138:141], v[162:165], v[58:61]
	v_mfma_f32_16x16x32_bf16 v[46:49], v[130:133], v[170:173], v[46:49]
	v_mfma_f32_16x16x32_bf16 v[42:45], v[138:141], v[170:173], v[42:45]
	v_mfma_f32_16x16x32_bf16 v[30:33], v[130:133], v[178:181], v[30:33]
	v_mfma_f32_16x16x32_bf16 v[26:29], v[138:141], v[178:181], v[26:29]
	v_mfma_f32_16x16x32_bf16 v[14:17], v[130:133], v[204:207], v[14:17]
	v_mfma_f32_16x16x32_bf16 v[10:13], v[138:141], v[204:207], v[10:13]
	v_mfma_f32_16x16x32_bf16 v[62:65], v[134:137], v[166:169], v[62:65]
	v_mfma_f32_16x16x32_bf16 v[58:61], v[142:145], v[166:169], v[58:61]
	v_mfma_f32_16x16x32_bf16 v[46:49], v[134:137], v[174:177], v[46:49]
	v_mfma_f32_16x16x32_bf16 v[42:45], v[142:145], v[174:177], v[42:45]
	v_mfma_f32_16x16x32_bf16 v[30:33], v[134:137], v[182:185], v[30:33]
	v_mfma_f32_16x16x32_bf16 v[26:29], v[142:145], v[182:185], v[26:29]
	v_mfma_f32_16x16x32_bf16 v[14:17], v[134:137], v[208:211], v[14:17]
	v_mfma_f32_16x16x32_bf16 v[10:13], v[142:145], v[208:211], v[10:13]
	v_mfma_f32_16x16x32_bf16 v[54:57], v[146:149], v[162:165], v[54:57]
	v_mfma_f32_16x16x32_bf16 v[50:53], v[154:157], v[162:165], v[50:53]
	v_mfma_f32_16x16x32_bf16 v[38:41], v[146:149], v[170:173], v[38:41]
	v_mfma_f32_16x16x32_bf16 v[34:37], v[154:157], v[170:173], v[34:37]
	v_mfma_f32_16x16x32_bf16 v[22:25], v[146:149], v[178:181], v[22:25]
	v_mfma_f32_16x16x32_bf16 v[18:21], v[154:157], v[178:181], v[18:21]
	v_mfma_f32_16x16x32_bf16 v[6:9], v[146:149], v[204:207], v[6:9]
	v_mfma_f32_16x16x32_bf16 v[2:5], v[154:157], v[204:207], v[2:5]
	v_mfma_f32_16x16x32_bf16 v[54:57], v[150:153], v[166:169], v[54:57]
	v_mfma_f32_16x16x32_bf16 v[50:53], v[158:161], v[166:169], v[50:53]
	v_mfma_f32_16x16x32_bf16 v[38:41], v[150:153], v[174:177], v[38:41]
	v_mfma_f32_16x16x32_bf16 v[34:37], v[158:161], v[174:177], v[34:37]
	v_mfma_f32_16x16x32_bf16 v[22:25], v[150:153], v[182:185], v[22:25]
	v_mfma_f32_16x16x32_bf16 v[18:21], v[158:161], v[182:185], v[18:21]
	v_mfma_f32_16x16x32_bf16 v[6:9], v[150:153], v[208:211], v[6:9]
	v_mfma_f32_16x16x32_bf16 v[2:5], v[158:161], v[208:211], v[2:5]
	s_setprio 0
	s_barrier
	s_add_i32 s81, s81, 2
	s_add_u32 s56, s56, 0x100
	s_addc_u32 s57, s57, 0
	s_add_u32 s77, s77, 0x100
	s_addc_u32 s78, s78, 0
	s_cmp_gt_u32 s81, 13
	s_cbranch_scc0 .LBB0_833
	s_and_b64 vcc, exec, s[52:53]
	s_cbranch_vccz .LBB0_836
	s_barrier

; #define PG8_STAGE(bufoff, gbase, voff) do { _Pragma("unroll") for (int _i = 0; _i < 2; ++_i) \
;         __builtin_amdgcn_global_load_lds((const unsigned*)((const char*)(gbase) + (voff)[_i]), (PG8_LAS unsigned*)(lds + (bufoff) + ldsw + _i * 8192), 16, 0, 0); } while (0)
; #define PG8_LDA(dst, b, h) do { _Pragma("unroll") for (int m = 0; m < 4; ++m) _Pragma("unroll") for (int k = 0; k < 2; ++k) dst[m][k] = *(const PG8_LAS bf16x8*)(lds + PG8_SA(b, h) + aoff + m * 2048 + k * 1024); } while (0)
; #define PG8_LDB(dst, b, h) do { _Pragma("unroll") for (int n = 0; n < 2; ++n) _Pragma("unroll") for (int k = 0; k < 2; ++k) dst[n][k] = *(const PG8_LAS bf16x8*)(lds + PG8_SB(b, h) + boff + n * 2048 + k * 1024); } while (0)
; #define PG8_MMA(ai, bj, At, Bt) do { __builtin_amdgcn_s_setprio(1); _Pragma("unroll") for (int m = 0; m < 4; ++m) _Pragma("unroll") for (int n = 0; n < 2; ++n) _Pragma("unroll") for (int k = 0; k < 2; ++k) \
;         acc[ai][bj][m][n] = __builtin_amdgcn_mfma_f32_16x16x32_bf16(Bt[n][k], At[m][k], acc[ai][bj][m][n], 0, 0, 0); __builtin_amdgcn_s_setprio(0); } while (0)
; #define PG8_WAIT_V(n) asm volatile("s_waitcnt vmcnt(" #n ")" ::: "memory")
; #define PG8_WAIT_L(n) asm volatile("s_waitcnt lgkmcnt(" #n ")" ::: "memory")
; #define PG8_BAR __builtin_amdgcn_s_barrier()
; #define PG8_SCHED __builtin_amdgcn_sched_barrier(0)
; template <class Epi, class Sched, bool ALIGN_EPI = false, bool SP2 = false>
; __device__ __forceinline__ void gemm_phase(PG8_LAS unsigned char* lds, const Gemm g, const Sched& S, const Epi& E) {
;     ...
;             PG8_LDB(B0, 0, 0); PG8_LDB(B1, 0, 1); PG8_SCHED; PG8_LDA(At, 0, 0); PG8_STAGE(PG8_SA(1, 1), a1 + hstep, voffA);
;             PG8_WAIT_V(8); PG8_WAIT_L(0); PG8_BAR; PG8_MMA(0, 0, At, B0); PG8_MMA(0, 1, At, B1); PG8_BAR; PG8_SCHED;
;             PG8_LDA(At, 0, 1); PG8_STAGE(PG8_SB(0, 0), b2, voffB); PG8_STAGE(PG8_SB(0, 1), b2 + hstep, voffB); PG8_STAGE(PG8_SA(0, 0), a2, voffA);
.LBB0_852:
	s_add_i32 s76, s74, 2
	s_add_u32 s34, s56, 0x80
	s_addc_u32 s35, s57, 0
	s_add_i32 s10, 0, 0x10000
	s_cmp_eq_u32 s82, s74
	s_cselect_b32 s75, s65, s35
	s_cselect_b32 s74, s64, s34
	v_add_u32_e32 v151, s10, v145
	s_cselect_b32 s35, s73, vcc_hi
	s_cselect_b32 s34, s72, vcc_lo
	s_add_i32 s11, 0, 0x14000
	ds_read_b128 v[140:143], v151
	ds_read_b128 v[152:155], v151 offset:1024
	ds_read_b128 v[156:159], v151 offset:2048
	ds_read_b128 v[160:163], v151 offset:3072
	v_add_u32_e32 v151, s11, v145
	ds_read_b128 v[164:167], v151
	ds_read_b128 v[168:171], v151 offset:1024
	ds_read_b128 v[172:175], v151 offset:2048
	ds_read_b128 v[176:179], v151 offset:3072
	v_lshl_add_u64 v[184:185], s[56:57], 0, v[136:137]
	s_add_i32 m0, s22, 0xc000
	ds_read_b128 v[180:183], v148
	ds_read_b128 v[194:197], v148 offset:1024
	ds_read_b128 v[198:201], v148 offset:2048
	ds_read_b128 v[202:205], v148 offset:3072
	ds_read_b128 v[206:209], v148 offset:4096
	ds_read_b128 v[210:213], v148 offset:5120
	ds_read_b128 v[214:217], v148 offset:6144
	ds_read_b128 v[218:221], v148 offset:7168
	global_load_lds_dwordx4 v[184:185], off
	v_lshl_add_u64 v[184:185], s[56:57], 0, v[138:139]
	s_add_i32 m0, s22, 0xe000
	s_nop 0
	global_load_lds_dwordx4 v[184:185], off
	s_waitcnt vmcnt(8)
	s_waitcnt lgkmcnt(0)
	s_barrier
	s_setprio 1
	s_waitcnt lgkmcnt(0)
	v_mfma_f32_16x16x32_bf16 v[126:129], v[140:143], v[180:183], v[126:129]
	v_mfma_f32_16x16x32_bf16 v[122:125], v[156:159], v[180:183], v[122:125]
	v_mfma_f32_16x16x32_bf16 v[110:113], v[140:143], v[198:201], v[110:113]
	v_mfma_f32_16x16x32_bf16 v[106:109], v[156:159], v[198:201], v[106:109]
	v_mfma_f32_16x16x32_bf16 v[94:97], v[140:143], v[206:209], v[94:97]
	v_mfma_f32_16x16x32_bf16 v[90:93], v[156:159], v[206:209], v[90:93]
	v_mfma_f32_16x16x32_bf16 v[78:81], v[140:143], v[214:217], v[78:81]
	v_mfma_f32_16x16x32_bf16 v[74:77], v[156:159], v[214:217], v[74:77]
	v_mfma_f32_16x16x32_bf16 v[126:129], v[152:155], v[194:197], v[126:129]
	v_mfma_f32_16x16x32_bf16 v[122:125], v[160:163], v[194:197], v[122:125]
	v_mfma_f32_16x16x32_bf16 v[110:113], v[152:155], v[202:205], v[110:113]
	v_mfma_f32_16x16x32_bf16 v[106:109], v[160:163], v[202:205], v[106:109]
	v_mfma_f32_16x16x32_bf16 v[94:97], v[152:155], v[210:213], v[94:97]
	v_mfma_f32_16x16x32_bf16 v[90:93], v[160:163], v[210:213], v[90:93]
	v_mfma_f32_16x16x32_bf16 v[78:81], v[152:155], v[218:221], v[78:81]
	v_mfma_f32_16x16x32_bf16 v[74:77], v[160:163], v[218:221], v[74:77]
	v_mfma_f32_16x16x32_bf16 v[118:121], v[164:167], v[180:183], v[118:121]
	v_mfma_f32_16x16x32_bf16 v[114:117], v[172:175], v[180:183], v[114:117]
	v_mfma_f32_16x16x32_bf16 v[102:105], v[164:167], v[198:201], v[102:105]
	v_mfma_f32_16x16x32_bf16 v[98:101], v[172:175], v[198:201], v[98:101]
	v_mfma_f32_16x16x32_bf16 v[86:89], v[164:167], v[206:209], v[86:89]
	v_mfma_f32_16x16x32_bf16 v[82:85], v[172:175], v[206:209], v[82:85]
	v_mfma_f32_16x16x32_bf16 v[70:73], v[164:167], v[214:217], v[70:73]
	v_mfma_f32_16x16x32_bf16 v[66:69], v[172:175], v[214:217], v[66:69]
	v_mfma_f32_16x16x32_bf16 v[118:121], v[168:171], v[194:197], v[118:121]
	v_mfma_f32_16x16x32_bf16 v[114:117], v[176:179], v[194:197], v[114:117]
	v_mfma_f32_16x16x32_bf16 v[102:105], v[168:171], v[202:205], v[102:105]
	v_mfma_f32_16x16x32_bf16 v[98:101], v[176:179], v[202:205], v[98:101]
	v_mfma_f32_16x16x32_bf16 v[86:89], v[168:171], v[210:213], v[86:89]
	v_mfma_f32_16x16x32_bf16 v[82:85], v[176:179], v[210:213], v[82:85]
	v_mfma_f32_16x16x32_bf16 v[70:73], v[168:171], v[218:221], v[70:73]
	v_mfma_f32_16x16x32_bf16 v[66:69], v[176:179], v[218:221], v[66:69]
	s_setprio 0
	s_barrier
	s_add_i32 s10, s10, s2
	v_lshl_add_u64 v[184:185], s[34:35], 0, v[186:187]
	s_mov_b32 m0, s10
	ds_read_b128 v[180:183], v148 offset:16384
	ds_read_b128 v[194:197], v148 offset:17408
	ds_read_b128 v[198:201], v148 offset:18432
	ds_read_b128 v[202:205], v148 offset:19456
	ds_read_b128 v[206:209], v148 offset:20480
	ds_read_b128 v[210:213], v148 offset:21504
	ds_read_b128 v[214:217], v148 offset:22528
	ds_read_b128 v[218:221], v148 offset:23552
	global_load_lds_dwordx4 v[184:185], off
	s_add_i32 m0, s10, 0x2000
	v_lshl_add_u64 v[222:223], s[34:35], 0, v[130:131]
	s_add_u32 s34, s34, s48
	s_addc_u32 s35, s35, s49
	s_add_i32 s10, s11, s2
	global_load_lds_dwordx4 v[222:223], off
	v_lshl_add_u64 v[232:233], s[34:35], 0, v[186:187]
	s_mov_b32 m0, s10
	v_lshl_add_u64 v[234:235], s[34:35], 0, v[130:131]
	global_load_lds_dwordx4 v[232:233], off
	s_add_i32 m0, s10, 0x2000
	v_lshl_add_u64 v[236:237], s[74:75], 0, v[134:135]
	global_load_lds_dwordx4 v[234:235], off
	s_mov_b32 m0, s22
	v_lshl_add_u64 v[238:239], s[74:75], 0, v[132:133]
	global_load_lds_dwordx4 v[236:237], off
	s_mov_b32 m0, s23
	s_nop 0
	global_load_lds_dwordx4 v[238:239], off
	s_waitcnt vmcnt(8)
	s_waitcnt lgkmcnt(0)
	s_barrier
; #define PG8_STAGE(bufoff, gbase, voff) do { _Pragma("unroll") for (int _i = 0; _i < 2; ++_i) \
;         __builtin_amdgcn_global_load_lds((const unsigned*)((const char*)(gbase) + (voff)[_i]), (PG8_LAS unsigned*)(lds + (bufoff) + ldsw + _i * 8192), 16, 0, 0); } while (0)
; #define PG8_LDA(dst, b, h) do { _Pragma("unroll") for (int m = 0; m < 4; ++m) _Pragma("unroll") for (int k = 0; k < 2; ++k) dst[m][k] = *(const PG8_LAS bf16x8*)(lds + PG8_SA(b, h) + aoff + m * 2048 + k * 1024); } while (0)
; #define PG8_LDB(dst, b, h) do { _Pragma("unroll") for (int n = 0; n < 2; ++n) _Pragma("unroll") for (int k = 0; k < 2; ++k) dst[n][k] = *(const PG8_LAS bf16x8*)(lds + PG8_SB(b, h) + boff + n * 2048 + k * 1024); } while (0)
; #define PG8_MMA(ai, bj, At, Bt) do { __builtin_amdgcn_s_setprio(1); _Pragma("unroll") for (int m = 0; m < 4; ++m) _Pragma("unroll") for (int n = 0; n < 2; ++n) _Pragma("unroll") for (int k = 0; k < 2; ++k) \
;         acc[ai][bj][m][n] = __builtin_amdgcn_mfma_f32_16x16x32_bf16(Bt[n][k], At[m][k], acc[ai][bj][m][n], 0, 0, 0); __builtin_amdgcn_s_setprio(0); } while (0)
; #define PG8_WAIT_V(n) asm volatile("s_waitcnt vmcnt(" #n ")" ::: "memory")
; #define PG8_WAIT_L(n) asm volatile("s_waitcnt lgkmcnt(" #n ")" ::: "memory")
; #define PG8_BAR __builtin_amdgcn_s_barrier()
; #define PG8_SCHED __builtin_amdgcn_sched_barrier(0)
; template <class Epi, class Sched, bool ALIGN_EPI = false, bool SP2 = false>
; __device__ __forceinline__ void gemm_phase(PG8_LAS unsigned char* lds, const Gemm g, const Sched& S, const Epi& E) {
;     ...
;             PG8_WAIT_V(8); PG8_WAIT_L(0); PG8_BAR; PG8_MMA(1, 0, At, B0); PG8_MMA(1, 1, At, B1); PG8_BAR; PG8_SCHED;
;             PG8_LDB(B0, 1, 0); PG8_LDB(B1, 1, 1); PG8_SCHED; PG8_LDA(At, 1, 0); PG8_STAGE(PG8_SA(0, 1), a2 + hstep, voffA);
;             PG8_WAIT_V(8); PG8_WAIT_L(0); PG8_BAR; PG8_MMA(0, 0, At, B0); PG8_MMA(0, 1, At, B1); PG8_BAR; PG8_SCHED;
	s_setprio 1
	s_waitcnt lgkmcnt(0)
	v_mfma_f32_16x16x32_bf16 v[62:65], v[140:143], v[180:183], v[62:65]
	v_mfma_f32_16x16x32_bf16 v[58:61], v[156:159], v[180:183], v[58:61]
	v_mfma_f32_16x16x32_bf16 v[46:49], v[140:143], v[198:201], v[46:49]
	v_mfma_f32_16x16x32_bf16 v[42:45], v[156:159], v[198:201], v[42:45]
	v_mfma_f32_16x16x32_bf16 v[30:33], v[140:143], v[206:209], v[30:33]
	v_mfma_f32_16x16x32_bf16 v[26:29], v[156:159], v[206:209], v[26:29]
	v_mfma_f32_16x16x32_bf16 v[14:17], v[140:143], v[214:217], v[14:17]
	v_mfma_f32_16x16x32_bf16 v[10:13], v[156:159], v[214:217], v[10:13]
	v_mfma_f32_16x16x32_bf16 v[62:65], v[152:155], v[194:197], v[62:65]
	v_mfma_f32_16x16x32_bf16 v[58:61], v[160:163], v[194:197], v[58:61]
	v_mfma_f32_16x16x32_bf16 v[46:49], v[152:155], v[202:205], v[46:49]
	v_mfma_f32_16x16x32_bf16 v[42:45], v[160:163], v[202:205], v[42:45]
	v_mfma_f32_16x16x32_bf16 v[30:33], v[152:155], v[210:213], v[30:33]
	v_mfma_f32_16x16x32_bf16 v[26:29], v[160:163], v[210:213], v[26:29]
	v_mfma_f32_16x16x32_bf16 v[14:17], v[152:155], v[218:221], v[14:17]
	v_mfma_f32_16x16x32_bf16 v[10:13], v[160:163], v[218:221], v[10:13]
	v_mfma_f32_16x16x32_bf16 v[54:57], v[164:167], v[180:183], v[54:57]
	v_mfma_f32_16x16x32_bf16 v[50:53], v[172:175], v[180:183], v[50:53]
	v_mfma_f32_16x16x32_bf16 v[38:41], v[164:167], v[198:201], v[38:41]
	v_mfma_f32_16x16x32_bf16 v[34:37], v[172:175], v[198:201], v[34:37]
	v_mfma_f32_16x16x32_bf16 v[22:25], v[164:167], v[206:209], v[22:25]
	v_mfma_f32_16x16x32_bf16 v[18:21], v[172:175], v[206:209], v[18:21]
	v_mfma_f32_16x16x32_bf16 v[6:9], v[164:167], v[214:217], v[6:9]
	v_mfma_f32_16x16x32_bf16 v[2:5], v[172:175], v[214:217], v[2:5]
	v_mfma_f32_16x16x32_bf16 v[54:57], v[168:171], v[194:197], v[54:57]
	v_mfma_f32_16x16x32_bf16 v[50:53], v[176:179], v[194:197], v[50:53]
	v_mfma_f32_16x16x32_bf16 v[38:41], v[168:171], v[202:205], v[38:41]
	v_mfma_f32_16x16x32_bf16 v[34:37], v[176:179], v[202:205], v[34:37]
	v_mfma_f32_16x16x32_bf16 v[22:25], v[168:171], v[210:213], v[22:25]
	v_mfma_f32_16x16x32_bf16 v[18:21], v[176:179], v[210:213], v[18:21]
	v_mfma_f32_16x16x32_bf16 v[6:9], v[168:171], v[218:221], v[6:9]
	v_mfma_f32_16x16x32_bf16 v[2:5], v[176:179], v[218:221], v[2:5]
	s_setprio 0
	s_barrier
	s_add_i32 s10, 0, 0x18000
	v_add_u32_e32 v151, s10, v145
	s_add_i32 s11, 0, 0x1c000
	ds_read_b128 v[140:143], v151
	ds_read_b128 v[152:155], v151 offset:1024
	ds_read_b128 v[156:159], v151 offset:2048
	ds_read_b128 v[160:163], v151 offset:3072
	v_add_u32_e32 v151, s11, v145
	ds_read_b128 v[164:167], v151
	ds_read_b128 v[168:171], v151 offset:1024
	ds_read_b128 v[172:175], v151 offset:2048
	ds_read_b128 v[176:179], v151 offset:3072
	s_add_u32 s34, s74, s48
	s_addc_u32 s35, s75, s49
	s_mov_b32 m0, s47
	v_lshl_add_u64 v[240:241], s[34:35], 0, v[134:135]
	ds_read_b128 v[180:183], v148 offset:32768
	ds_read_b128 v[194:197], v148 offset:33792
	ds_read_b128 v[198:201], v148 offset:34816
	ds_read_b128 v[202:205], v148 offset:35840
	ds_read_b128 v[206:209], v148 offset:36864
	ds_read_b128 v[210:213], v148 offset:37888
	ds_read_b128 v[214:217], v148 offset:38912
	ds_read_b128 v[218:221], v148 offset:39936
	global_load_lds_dwordx4 v[240:241], off
	v_lshl_add_u64 v[240:241], s[34:35], 0, v[132:133]
	s_mov_b32 m0, s51
	s_nop 0
	global_load_lds_dwordx4 v[240:241], off
	s_waitcnt vmcnt(8)
	s_waitcnt lgkmcnt(0)
	s_barrier
	s_setprio 1
	s_waitcnt lgkmcnt(0)
	v_mfma_f32_16x16x32_bf16 v[126:129], v[140:143], v[180:183], v[126:129]
	v_mfma_f32_16x16x32_bf16 v[122:125], v[156:159], v[180:183], v[122:125]
	v_mfma_f32_16x16x32_bf16 v[110:113], v[140:143], v[198:201], v[110:113]
	v_mfma_f32_16x16x32_bf16 v[106:109], v[156:159], v[198:201], v[106:109]
	v_mfma_f32_16x16x32_bf16 v[94:97], v[140:143], v[206:209], v[94:97]
	v_mfma_f32_16x16x32_bf16 v[90:93], v[156:159], v[206:209], v[90:93]
	v_mfma_f32_16x16x32_bf16 v[78:81], v[140:143], v[214:217], v[78:81]
	v_mfma_f32_16x16x32_bf16 v[74:77], v[156:159], v[214:217], v[74:77]
	v_mfma_f32_16x16x32_bf16 v[126:129], v[152:155], v[194:197], v[126:129]
	v_mfma_f32_16x16x32_bf16 v[122:125], v[160:163], v[194:197], v[122:125]
	v_mfma_f32_16x16x32_bf16 v[110:113], v[152:155], v[202:205], v[110:113]
	v_mfma_f32_16x16x32_bf16 v[106:109], v[160:163], v[202:205], v[106:109]
	v_mfma_f32_16x16x32_bf16 v[94:97], v[152:155], v[210:213], v[94:97]
	v_mfma_f32_16x16x32_bf16 v[90:93], v[160:163], v[210:213], v[90:93]
	v_mfma_f32_16x16x32_bf16 v[78:81], v[152:155], v[218:221], v[78:81]
	v_mfma_f32_16x16x32_bf16 v[74:77], v[160:163], v[218:221], v[74:77]
	v_mfma_f32_16x16x32_bf16 v[118:121], v[164:167], v[180:183], v[118:121]
	v_mfma_f32_16x16x32_bf16 v[114:117], v[172:175], v[180:183], v[114:117]
	v_mfma_f32_16x16x32_bf16 v[102:105], v[164:167], v[198:201], v[102:105]
	v_mfma_f32_16x16x32_bf16 v[98:101], v[172:175], v[198:201], v[98:101]
	v_mfma_f32_16x16x32_bf16 v[86:89], v[164:167], v[206:209], v[86:89]
	v_mfma_f32_16x16x32_bf16 v[82:85], v[172:175], v[206:209], v[82:85]
	v_mfma_f32_16x16x32_bf16 v[70:73], v[164:167], v[214:217], v[70:73]
	v_mfma_f32_16x16x32_bf16 v[66:69], v[172:175], v[214:217], v[66:69]
	v_mfma_f32_16x16x32_bf16 v[118:121], v[168:171], v[194:197], v[118:121]
	v_mfma_f32_16x16x32_bf16 v[114:117], v[176:179], v[194:197], v[114:117]
	v_mfma_f32_16x16x32_bf16 v[102:105], v[168:171], v[202:205], v[102:105]
	v_mfma_f32_16x16x32_bf16 v[98:101], v[176:179], v[202:205], v[98:101]
	v_mfma_f32_16x16x32_bf16 v[86:89], v[168:171], v[210:213], v[86:89]
	v_mfma_f32_16x16x32_bf16 v[82:85], v[176:179], v[210:213], v[82:85]
	v_mfma_f32_16x16x32_bf16 v[70:73], v[168:171], v[218:221], v[70:73]
	v_mfma_f32_16x16x32_bf16 v[66:69], v[176:179], v[218:221], v[66:69]
	s_setprio 0
	s_barrier
; #define PG8_STAGE(bufoff, gbase, voff) do { _Pragma("unroll") for (int _i = 0; _i < 2; ++_i) \
;         __builtin_amdgcn_global_load_lds((const unsigned*)((const char*)(gbase) + (voff)[_i]), (PG8_LAS unsigned*)(lds + (bufoff) + ldsw + _i * 8192), 16, 0, 0); } while (0)
; #define PG8_LDA(dst, b, h) do { _Pragma("unroll") for (int m = 0; m < 4; ++m) _Pragma("unroll") for (int k = 0; k < 2; ++k) dst[m][k] = *(const PG8_LAS bf16x8*)(lds + PG8_SA(b, h) + aoff + m * 2048 + k * 1024); } while (0)
; #define PG8_MMA(ai, bj, At, Bt) do { __builtin_amdgcn_s_setprio(1); _Pragma("unroll") for (int m = 0; m < 4; ++m) _Pragma("unroll") for (int n = 0; n < 2; ++n) _Pragma("unroll") for (int k = 0; k < 2; ++k) \
;         acc[ai][bj][m][n] = __builtin_amdgcn_mfma_f32_16x16x32_bf16(Bt[n][k], At[m][k], acc[ai][bj][m][n], 0, 0, 0); __builtin_amdgcn_s_setprio(0); } while (0)
; #define PG8_WAIT_V(n) asm volatile("s_waitcnt vmcnt(" #n ")" ::: "memory")
; #define PG8_WAIT_L(n) asm volatile("s_waitcnt lgkmcnt(" #n ")" ::: "memory")
; #define PG8_BAR __builtin_amdgcn_s_barrier()
; #define PG8_SCHED __builtin_amdgcn_sched_barrier(0)
; template <class Epi, class Sched, bool ALIGN_EPI = false, bool SP2 = false>
; __device__ __forceinline__ void gemm_phase(PG8_LAS unsigned char* lds, const Gemm g, const Sched& S, const Epi& E) {
;     ...
;             PG8_LDA(At, 1, 1); PG8_STAGE(PG8_SB(1, 0), b3, voffB); PG8_STAGE(PG8_SB(1, 1), b3 + hstep, voffB); PG8_STAGE(PG8_SA(1, 0), a3, voffA);
;             PG8_WAIT_V(8); PG8_WAIT_L(0); PG8_BAR; PG8_MMA(1, 0, At, B0); PG8_MMA(1, 1, At, B1); PG8_BAR; PG8_SCHED;
	s_add_i32 s10, s10, s2
	v_lshl_add_u64 v[184:185], v[184:185], 0, s[44:45]
	s_mov_b32 m0, s10
	ds_read_b128 v[180:183], v148 offset:49152
	ds_read_b128 v[194:197], v148 offset:50176
	ds_read_b128 v[198:201], v148 offset:51200
	ds_read_b128 v[202:205], v148 offset:52224
	ds_read_b128 v[206:209], v148 offset:53248
	ds_read_b128 v[210:213], v148 offset:54272
	ds_read_b128 v[214:217], v148 offset:55296
	ds_read_b128 v[218:221], v148 offset:56320
	global_load_lds_dwordx4 v[184:185], off
	v_lshl_add_u64 v[184:185], v[222:223], 0, s[44:45]
	s_add_i32 m0, s10, 0x2000
	s_add_i32 s10, s11, s2
	global_load_lds_dwordx4 v[184:185], off
	v_lshl_add_u64 v[184:185], v[232:233], 0, s[44:45]
	s_mov_b32 m0, s10
	s_nop 0
	global_load_lds_dwordx4 v[184:185], off
	v_lshl_add_u64 v[184:185], v[234:235], 0, s[44:45]
	s_add_i32 m0, s10, 0x2000
	s_nop 0
	global_load_lds_dwordx4 v[184:185], off
	v_lshl_add_u64 v[184:185], v[236:237], 0, s[44:45]
	s_mov_b32 m0, s43
	s_nop 0
	global_load_lds_dwordx4 v[184:185], off
	v_lshl_add_u64 v[184:185], v[238:239], 0, s[44:45]
	s_mov_b32 m0, s83
	s_nop 0
	global_load_lds_dwordx4 v[184:185], off
	s_waitcnt vmcnt(8)
	s_waitcnt lgkmcnt(0)
	s_barrier
	s_setprio 1
	s_waitcnt lgkmcnt(0)
	v_mfma_f32_16x16x32_bf16 v[62:65], v[140:143], v[180:183], v[62:65]
	v_mfma_f32_16x16x32_bf16 v[58:61], v[156:159], v[180:183], v[58:61]
	v_mfma_f32_16x16x32_bf16 v[46:49], v[140:143], v[198:201], v[46:49]
	v_mfma_f32_16x16x32_bf16 v[42:45], v[156:159], v[198:201], v[42:45]
	v_mfma_f32_16x16x32_bf16 v[30:33], v[140:143], v[206:209], v[30:33]
	v_mfma_f32_16x16x32_bf16 v[26:29], v[156:159], v[206:209], v[26:29]
	v_mfma_f32_16x16x32_bf16 v[14:17], v[140:143], v[214:217], v[14:17]
	v_mfma_f32_16x16x32_bf16 v[10:13], v[156:159], v[214:217], v[10:13]
	v_mfma_f32_16x16x32_bf16 v[62:65], v[152:155], v[194:197], v[62:65]
	v_mfma_f32_16x16x32_bf16 v[58:61], v[160:163], v[194:197], v[58:61]
	v_mfma_f32_16x16x32_bf16 v[46:49], v[152:155], v[202:205], v[46:49]
	v_mfma_f32_16x16x32_bf16 v[42:45], v[160:163], v[202:205], v[42:45]
	v_mfma_f32_16x16x32_bf16 v[30:33], v[152:155], v[210:213], v[30:33]
	v_mfma_f32_16x16x32_bf16 v[26:29], v[160:163], v[210:213], v[26:29]
	v_mfma_f32_16x16x32_bf16 v[14:17], v[152:155], v[218:221], v[14:17]
	v_mfma_f32_16x16x32_bf16 v[10:13], v[160:163], v[218:221], v[10:13]
	v_mfma_f32_16x16x32_bf16 v[54:57], v[164:167], v[180:183], v[54:57]
	v_mfma_f32_16x16x32_bf16 v[50:53], v[172:175], v[180:183], v[50:53]
	v_mfma_f32_16x16x32_bf16 v[38:41], v[164:167], v[198:201], v[38:41]
	v_mfma_f32_16x16x32_bf16 v[34:37], v[172:175], v[198:201], v[34:37]
	v_mfma_f32_16x16x32_bf16 v[22:25], v[164:167], v[206:209], v[22:25]
	v_mfma_f32_16x16x32_bf16 v[18:21], v[172:175], v[206:209], v[18:21]
	v_mfma_f32_16x16x32_bf16 v[6:9], v[164:167], v[214:217], v[6:9]
	v_mfma_f32_16x16x32_bf16 v[2:5], v[172:175], v[214:217], v[2:5]
	v_mfma_f32_16x16x32_bf16 v[54:57], v[168:171], v[194:197], v[54:57]
	v_mfma_f32_16x16x32_bf16 v[50:53], v[176:179], v[194:197], v[50:53]
	v_mfma_f32_16x16x32_bf16 v[38:41], v[168:171], v[202:205], v[38:41]
	v_mfma_f32_16x16x32_bf16 v[34:37], v[176:179], v[202:205], v[34:37]
	v_mfma_f32_16x16x32_bf16 v[22:25], v[168:171], v[210:213], v[22:25]
	v_mfma_f32_16x16x32_bf16 v[18:21], v[176:179], v[210:213], v[18:21]
	v_mfma_f32_16x16x32_bf16 v[6:9], v[168:171], v[218:221], v[6:9]
	v_mfma_f32_16x16x32_bf16 v[2:5], v[176:179], v[218:221], v[2:5]
	s_setprio 0
	s_barrier
	s_add_u32 s56, s56, 0x100
	s_addc_u32 s57, s57, 0
	s_add_u32 vcc_lo, vcc_lo, 0x100
	s_addc_u32 vcc_hi, vcc_hi, 0
	s_cmp_ge_i32 s76, s50
	s_mov_b32 s74, s76
	s_cbranch_scc0 .LBB0_852

; #define PG8_STAGE(bufoff, gbase, voff) do { _Pragma("unroll") for (int _i = 0; _i < 2; ++_i) \
;         __builtin_amdgcn_global_load_lds((const unsigned*)((const char*)(gbase) + (voff)[_i]), (PG8_LAS unsigned*)(lds + (bufoff) + ldsw + _i * 8192), 16, 0, 0); } while (0)
; #define PG8_LDA(dst, b, h) do { _Pragma("unroll") for (int m = 0; m < 4; ++m) _Pragma("unroll") for (int k = 0; k < 2; ++k) dst[m][k] = *(const PG8_LAS bf16x8*)(lds + PG8_SA(b, h) + aoff + m * 2048 + k * 1024); } while (0)
; #define PG8_LDB(dst, b, h) do { _Pragma("unroll") for (int n = 0; n < 2; ++n) _Pragma("unroll") for (int k = 0; k < 2; ++k) dst[n][k] = *(const PG8_LAS bf16x8*)(lds + PG8_SB(b, h) + boff + n * 2048 + k * 1024); } while (0)
; #define PG8_MMA(ai, bj, At, Bt) do { __builtin_amdgcn_s_setprio(1); _Pragma("unroll") for (int m = 0; m < 4; ++m) _Pragma("unroll") for (int n = 0; n < 2; ++n) _Pragma("unroll") for (int k = 0; k < 2; ++k) \
;         acc[ai][bj][m][n] = __builtin_amdgcn_mfma_f32_16x16x32_bf16(Bt[n][k], At[m][k], acc[ai][bj][m][n], 0, 0, 0); __builtin_amdgcn_s_setprio(0); } while (0)
; #define PG8_WAIT_V(n) asm volatile("s_waitcnt vmcnt(" #n ")" ::: "memory")
; #define PG8_WAIT_L(n) asm volatile("s_waitcnt lgkmcnt(" #n ")" ::: "memory")
; #define PG8_BAR __builtin_amdgcn_s_barrier()
; #define PG8_SCHED __builtin_amdgcn_sched_barrier(0)
; template <class Epi, class Sched, bool ALIGN_EPI = false, bool SP2 = false>
; __device__ __forceinline__ void gemm_phase(PG8_LAS unsigned char* lds, const Gemm g, const Sched& S, const Epi& E) {
;     ...
;             PG8_LDB(B0, 0, 0); PG8_LDB(B1, 0, 1); PG8_SCHED; PG8_LDA(At, 0, 0); PG8_STAGE(PG8_SA(1, 1), a1 + hstep, voffA);
;             PG8_WAIT_V(8); PG8_WAIT_L(0); PG8_BAR; PG8_MMA(0, 0, At, B0); PG8_MMA(0, 1, At, B1); PG8_BAR; PG8_SCHED;
;             PG8_LDA(At, 0, 1); PG8_STAGE(PG8_SB(0, 0), b2, voffB); PG8_STAGE(PG8_SB(0, 1), b2 + hstep, voffB); PG8_STAGE(PG8_SA(0, 0), a2, voffA);
.LBB0_900:
	s_add_u32 s10, s56, 0xfffc0080
	s_addc_u32 s11, s57, -1
	s_add_i32 s34, 0, 0x10000
	s_cmp_eq_u32 s59, 12
	s_cselect_b32 s65, s9, s11
	s_cselect_b32 s64, s42, s10
	s_cselect_b32 s63, s43, s53
	s_cselect_b32 s62, s50, s51
	s_add_i32 s10, 0, 0x14000
	v_add_u32_e32 v152, s34, v199
	v_add_u32_e32 v168, s10, v199
	ds_read_b128 v[26:29], v152
	ds_read_b128 v[38:41], v152 offset:1024
	ds_read_b128 v[148:151], v152 offset:2048
	ds_read_b128 v[152:155], v152 offset:3072
	ds_read_b128 v[156:159], v168
	ds_read_b128 v[160:163], v168 offset:1024
	ds_read_b128 v[164:167], v168 offset:2048
	ds_read_b128 v[168:171], v168 offset:3072
	v_lshl_add_u64 v[184:185], s[56:57], 0, v[144:145]
	s_add_i32 m0, s47, 0xc000
	ds_read_b128 v[172:175], v207
	ds_read_b128 v[176:179], v207 offset:1024
	ds_read_b128 v[180:183], v207 offset:2048
	ds_read_b128 v[194:197], v207 offset:3072
	ds_read_b128 v[200:203], v207 offset:4096
	ds_read_b128 v[210:213], v207 offset:5120
	ds_read_b128 v[214:217], v207 offset:6144
	ds_read_b128 v[218:221], v207 offset:7168
	global_load_lds_dwordx4 v[184:185], off
	v_lshl_add_u64 v[184:185], s[56:57], 0, v[146:147]
	s_add_i32 m0, s47, 0xe000
	s_nop 0
	global_load_lds_dwordx4 v[184:185], off
	s_waitcnt vmcnt(8)
	s_waitcnt lgkmcnt(0)
	s_barrier
	s_setprio 1
	s_waitcnt lgkmcnt(0)
	v_mfma_f32_16x16x32_bf16 v[134:137], v[26:29], v[172:175], v[134:137]
	v_mfma_f32_16x16x32_bf16 v[130:133], v[148:151], v[172:175], v[130:133]
	v_mfma_f32_16x16x32_bf16 v[118:121], v[26:29], v[180:183], v[118:121]
	v_mfma_f32_16x16x32_bf16 v[114:117], v[148:151], v[180:183], v[114:117]
	v_mfma_f32_16x16x32_bf16 v[102:105], v[26:29], v[200:203], v[102:105]
	v_mfma_f32_16x16x32_bf16 v[98:101], v[148:151], v[200:203], v[98:101]
	v_mfma_f32_16x16x32_bf16 v[86:89], v[26:29], v[214:217], v[86:89]
	v_mfma_f32_16x16x32_bf16 v[82:85], v[148:151], v[214:217], v[82:85]
	v_mfma_f32_16x16x32_bf16 v[134:137], v[38:41], v[176:179], v[134:137]
	v_mfma_f32_16x16x32_bf16 v[130:133], v[152:155], v[176:179], v[130:133]
	v_mfma_f32_16x16x32_bf16 v[118:121], v[38:41], v[194:197], v[118:121]
	v_mfma_f32_16x16x32_bf16 v[114:117], v[152:155], v[194:197], v[114:117]
	v_mfma_f32_16x16x32_bf16 v[102:105], v[38:41], v[210:213], v[102:105]
	v_mfma_f32_16x16x32_bf16 v[98:101], v[152:155], v[210:213], v[98:101]
	v_mfma_f32_16x16x32_bf16 v[86:89], v[38:41], v[218:221], v[86:89]
	v_mfma_f32_16x16x32_bf16 v[82:85], v[152:155], v[218:221], v[82:85]
	v_mfma_f32_16x16x32_bf16 v[126:129], v[156:159], v[172:175], v[126:129]
	v_mfma_f32_16x16x32_bf16 v[122:125], v[164:167], v[172:175], v[122:125]
	v_mfma_f32_16x16x32_bf16 v[110:113], v[156:159], v[180:183], v[110:113]
	v_mfma_f32_16x16x32_bf16 v[106:109], v[164:167], v[180:183], v[106:109]
	v_mfma_f32_16x16x32_bf16 v[94:97], v[156:159], v[200:203], v[94:97]
	v_mfma_f32_16x16x32_bf16 v[90:93], v[164:167], v[200:203], v[90:93]
	v_mfma_f32_16x16x32_bf16 v[78:81], v[156:159], v[214:217], v[78:81]
	v_mfma_f32_16x16x32_bf16 v[74:77], v[164:167], v[214:217], v[74:77]
	v_mfma_f32_16x16x32_bf16 v[126:129], v[160:163], v[176:179], v[126:129]
	v_mfma_f32_16x16x32_bf16 v[122:125], v[168:171], v[176:179], v[122:125]
	v_mfma_f32_16x16x32_bf16 v[110:113], v[160:163], v[194:197], v[110:113]
	v_mfma_f32_16x16x32_bf16 v[106:109], v[168:171], v[194:197], v[106:109]
	v_mfma_f32_16x16x32_bf16 v[94:97], v[160:163], v[210:213], v[94:97]
	v_mfma_f32_16x16x32_bf16 v[90:93], v[168:171], v[210:213], v[90:93]
	v_mfma_f32_16x16x32_bf16 v[78:81], v[160:163], v[218:221], v[78:81]
	v_mfma_f32_16x16x32_bf16 v[74:77], v[168:171], v[218:221], v[74:77]
	s_setprio 0
	s_barrier
	s_add_i32 s11, s34, s66
	v_lshl_add_u64 v[184:185], s[62:63], 0, v[142:143]
	s_mov_b32 m0, s11
	ds_read_b128 v[172:175], v207 offset:16384
	ds_read_b128 v[176:179], v207 offset:17408
	ds_read_b128 v[180:183], v207 offset:18432
	ds_read_b128 v[194:197], v207 offset:19456
	ds_read_b128 v[200:203], v207 offset:20480
	ds_read_b128 v[210:213], v207 offset:21504
	ds_read_b128 v[214:217], v207 offset:22528
	ds_read_b128 v[218:221], v207 offset:23552
	global_load_lds_dwordx4 v[184:185], off
	s_add_i32 m0, s11, 0x2000
	s_add_u32 s34, s62, 0x40000
	v_lshl_add_u64 v[222:223], s[62:63], 0, v[138:139]
	s_addc_u32 s35, s63, 0
	s_add_i32 s10, s10, s66
	global_load_lds_dwordx4 v[222:223], off
	v_lshl_add_u64 v[232:233], s[34:35], 0, v[142:143]
	s_mov_b32 m0, s10
	v_lshl_add_u64 v[234:235], s[64:65], 0, v[140:141]
	global_load_lds_dwordx4 v[232:233], off
	v_lshl_add_u64 v[232:233], s[34:35], 0, v[138:139]
	s_add_i32 m0, s10, 0x2000
	s_nop 0
	global_load_lds_dwordx4 v[232:233], off
	v_lshl_add_u64 v[232:233], s[64:65], 0, v[186:187]
	s_mov_b32 m0, s47
	s_nop 0
	global_load_lds_dwordx4 v[232:233], off
	s_mov_b32 m0, s67
	s_nop 0
	global_load_lds_dwordx4 v[234:235], off
	s_waitcnt vmcnt(8)
	s_waitcnt lgkmcnt(0)
	s_barrier
; #define PG8_STAGE(bufoff, gbase, voff) do { _Pragma("unroll") for (int _i = 0; _i < 2; ++_i) \
;         __builtin_amdgcn_global_load_lds((const unsigned*)((const char*)(gbase) + (voff)[_i]), (PG8_LAS unsigned*)(lds + (bufoff) + ldsw + _i * 8192), 16, 0, 0); } while (0)
; #define PG8_LDA(dst, b, h) do { _Pragma("unroll") for (int m = 0; m < 4; ++m) _Pragma("unroll") for (int k = 0; k < 2; ++k) dst[m][k] = *(const PG8_LAS bf16x8*)(lds + PG8_SA(b, h) + aoff + m * 2048 + k * 1024); } while (0)
; #define PG8_LDB(dst, b, h) do { _Pragma("unroll") for (int n = 0; n < 2; ++n) _Pragma("unroll") for (int k = 0; k < 2; ++k) dst[n][k] = *(const PG8_LAS bf16x8*)(lds + PG8_SB(b, h) + boff + n * 2048 + k * 1024); } while (0)
; #define PG8_MMA(ai, bj, At, Bt) do { __builtin_amdgcn_s_setprio(1); _Pragma("unroll") for (int m = 0; m < 4; ++m) _Pragma("unroll") for (int n = 0; n < 2; ++n) _Pragma("unroll") for (int k = 0; k < 2; ++k) \
;         acc[ai][bj][m][n] = __builtin_amdgcn_mfma_f32_16x16x32_bf16(Bt[n][k], At[m][k], acc[ai][bj][m][n], 0, 0, 0); __builtin_amdgcn_s_setprio(0); } while (0)
; #define PG8_WAIT_V(n) asm volatile("s_waitcnt vmcnt(" #n ")" ::: "memory")
; #define PG8_WAIT_L(n) asm volatile("s_waitcnt lgkmcnt(" #n ")" ::: "memory")
; #define PG8_BAR __builtin_amdgcn_s_barrier()
; #define PG8_SCHED __builtin_amdgcn_sched_barrier(0)
; template <class Epi, class Sched, bool ALIGN_EPI = false, bool SP2 = false>
; __device__ __forceinline__ void gemm_phase(PG8_LAS unsigned char* lds, const Gemm g, const Sched& S, const Epi& E) {
;     ...
;             PG8_WAIT_V(8); PG8_WAIT_L(0); PG8_BAR; PG8_MMA(1, 0, At, B0); PG8_MMA(1, 1, At, B1); PG8_BAR; PG8_SCHED;
;             PG8_LDB(B0, 1, 0); PG8_LDB(B1, 1, 1); PG8_SCHED; PG8_LDA(At, 1, 0); PG8_STAGE(PG8_SA(0, 1), a2 + hstep, voffA);
;             PG8_WAIT_V(8); PG8_WAIT_L(0); PG8_BAR; PG8_MMA(0, 0, At, B0); PG8_MMA(0, 1, At, B1); PG8_BAR; PG8_SCHED;
	s_setprio 1
	s_waitcnt lgkmcnt(0)
	v_mfma_f32_16x16x32_bf16 v[70:73], v[26:29], v[172:175], v[70:73]
	v_mfma_f32_16x16x32_bf16 v[66:69], v[148:151], v[172:175], v[66:69]
	v_mfma_f32_16x16x32_bf16 v[54:57], v[26:29], v[180:183], v[54:57]
	v_mfma_f32_16x16x32_bf16 v[50:53], v[148:151], v[180:183], v[50:53]
	v_mfma_f32_16x16x32_bf16 v[34:37], v[26:29], v[200:203], v[34:37]
	v_mfma_f32_16x16x32_bf16 v[30:33], v[148:151], v[200:203], v[30:33]
	v_mfma_f32_16x16x32_bf16 v[14:17], v[26:29], v[214:217], v[14:17]
	v_mfma_f32_16x16x32_bf16 v[10:13], v[148:151], v[214:217], v[10:13]
	v_mfma_f32_16x16x32_bf16 v[70:73], v[38:41], v[176:179], v[70:73]
	v_mfma_f32_16x16x32_bf16 v[66:69], v[152:155], v[176:179], v[66:69]
	v_mfma_f32_16x16x32_bf16 v[54:57], v[38:41], v[194:197], v[54:57]
	v_mfma_f32_16x16x32_bf16 v[50:53], v[152:155], v[194:197], v[50:53]
	v_mfma_f32_16x16x32_bf16 v[34:37], v[38:41], v[210:213], v[34:37]
	v_mfma_f32_16x16x32_bf16 v[30:33], v[152:155], v[210:213], v[30:33]
	v_mfma_f32_16x16x32_bf16 v[14:17], v[38:41], v[218:221], v[14:17]
	v_mfma_f32_16x16x32_bf16 v[10:13], v[152:155], v[218:221], v[10:13]
	v_mfma_f32_16x16x32_bf16 v[46:49], v[156:159], v[180:183], v[46:49]
	v_mfma_f32_16x16x32_bf16 v[42:45], v[164:167], v[180:183], v[42:45]
	v_mfma_f32_16x16x32_bf16 v[22:25], v[156:159], v[200:203], v[22:25]
	v_mfma_f32_16x16x32_bf16 v[18:21], v[164:167], v[200:203], v[18:21]
	v_mfma_f32_16x16x32_bf16 v[6:9], v[156:159], v[214:217], v[6:9]
	v_mfma_f32_16x16x32_bf16 v[2:5], v[164:167], v[214:217], v[2:5]
	v_mfma_f32_16x16x32_bf16 v[26:29], v[156:159], v[172:175], v[62:65]
	v_mfma_f32_16x16x32_bf16 v[38:41], v[164:167], v[172:175], v[58:61]
	v_mfma_f32_16x16x32_bf16 v[46:49], v[160:163], v[194:197], v[46:49]
	v_mfma_f32_16x16x32_bf16 v[42:45], v[168:171], v[194:197], v[42:45]
	v_mfma_f32_16x16x32_bf16 v[22:25], v[160:163], v[210:213], v[22:25]
	v_mfma_f32_16x16x32_bf16 v[18:21], v[168:171], v[210:213], v[18:21]
	v_mfma_f32_16x16x32_bf16 v[6:9], v[160:163], v[218:221], v[6:9]
	v_mfma_f32_16x16x32_bf16 v[2:5], v[168:171], v[218:221], v[2:5]
	v_mfma_f32_16x16x32_bf16 v[26:29], v[160:163], v[176:179], v[26:29]
	v_mfma_f32_16x16x32_bf16 v[38:41], v[168:171], v[176:179], v[38:41]
	s_setprio 0
	s_barrier
	s_add_i32 s10, 0, 0x18000
	s_add_i32 s11, 0, 0x1c000
	v_add_u32_e32 v152, s10, v199
	v_add_u32_e32 v168, s11, v199
	ds_read_b128 v[58:61], v152
	ds_read_b128 v[62:65], v152 offset:1024
	ds_read_b128 v[148:151], v152 offset:2048
	ds_read_b128 v[152:155], v152 offset:3072
	ds_read_b128 v[156:159], v168
	ds_read_b128 v[160:163], v168 offset:1024
	ds_read_b128 v[164:167], v168 offset:2048
	ds_read_b128 v[168:171], v168 offset:3072
	s_add_u32 s34, s64, 0x40000
	s_addc_u32 s35, s65, 0
	s_mov_b32 m0, s72
	v_lshl_add_u64 v[236:237], s[34:35], 0, v[186:187]
	ds_read_b128 v[172:175], v207 offset:32768
	ds_read_b128 v[176:179], v207 offset:33792
	ds_read_b128 v[180:183], v207 offset:34816
	ds_read_b128 v[194:197], v207 offset:35840
	ds_read_b128 v[200:203], v207 offset:36864
	ds_read_b128 v[210:213], v207 offset:37888
	ds_read_b128 v[214:217], v207 offset:38912
	ds_read_b128 v[218:221], v207 offset:39936
	global_load_lds_dwordx4 v[236:237], off
	v_lshl_add_u64 v[236:237], s[34:35], 0, v[140:141]
	s_mov_b32 m0, s73
	s_nop 0
	global_load_lds_dwordx4 v[236:237], off
	s_waitcnt vmcnt(8)
	s_waitcnt lgkmcnt(0)
	s_barrier
	s_setprio 1
	s_waitcnt lgkmcnt(0)
	v_mfma_f32_16x16x32_bf16 v[134:137], v[58:61], v[172:175], v[134:137]
	v_mfma_f32_16x16x32_bf16 v[130:133], v[148:151], v[172:175], v[130:133]
	v_mfma_f32_16x16x32_bf16 v[118:121], v[58:61], v[180:183], v[118:121]
	v_mfma_f32_16x16x32_bf16 v[114:117], v[148:151], v[180:183], v[114:117]
	v_mfma_f32_16x16x32_bf16 v[102:105], v[58:61], v[200:203], v[102:105]
	v_mfma_f32_16x16x32_bf16 v[98:101], v[148:151], v[200:203], v[98:101]
	v_mfma_f32_16x16x32_bf16 v[86:89], v[58:61], v[214:217], v[86:89]
	v_mfma_f32_16x16x32_bf16 v[82:85], v[148:151], v[214:217], v[82:85]
	v_mfma_f32_16x16x32_bf16 v[134:137], v[62:65], v[176:179], v[134:137]
	v_mfma_f32_16x16x32_bf16 v[130:133], v[152:155], v[176:179], v[130:133]
	v_mfma_f32_16x16x32_bf16 v[118:121], v[62:65], v[194:197], v[118:121]
	v_mfma_f32_16x16x32_bf16 v[114:117], v[152:155], v[194:197], v[114:117]
	v_mfma_f32_16x16x32_bf16 v[102:105], v[62:65], v[210:213], v[102:105]
	v_mfma_f32_16x16x32_bf16 v[98:101], v[152:155], v[210:213], v[98:101]
	v_mfma_f32_16x16x32_bf16 v[86:89], v[62:65], v[218:221], v[86:89]
	v_mfma_f32_16x16x32_bf16 v[82:85], v[152:155], v[218:221], v[82:85]
	v_mfma_f32_16x16x32_bf16 v[126:129], v[156:159], v[172:175], v[126:129]
	v_mfma_f32_16x16x32_bf16 v[122:125], v[164:167], v[172:175], v[122:125]
	v_mfma_f32_16x16x32_bf16 v[110:113], v[156:159], v[180:183], v[110:113]
	v_mfma_f32_16x16x32_bf16 v[106:109], v[164:167], v[180:183], v[106:109]
	v_mfma_f32_16x16x32_bf16 v[94:97], v[156:159], v[200:203], v[94:97]
	v_mfma_f32_16x16x32_bf16 v[90:93], v[164:167], v[200:203], v[90:93]
	v_mfma_f32_16x16x32_bf16 v[78:81], v[156:159], v[214:217], v[78:81]
	v_mfma_f32_16x16x32_bf16 v[74:77], v[164:167], v[214:217], v[74:77]
	v_mfma_f32_16x16x32_bf16 v[126:129], v[160:163], v[176:179], v[126:129]
	v_mfma_f32_16x16x32_bf16 v[122:125], v[168:171], v[176:179], v[122:125]
	v_mfma_f32_16x16x32_bf16 v[110:113], v[160:163], v[194:197], v[110:113]
	v_mfma_f32_16x16x32_bf16 v[106:109], v[168:171], v[194:197], v[106:109]
	v_mfma_f32_16x16x32_bf16 v[94:97], v[160:163], v[210:213], v[94:97]
	v_mfma_f32_16x16x32_bf16 v[90:93], v[168:171], v[210:213], v[90:93]
	v_mfma_f32_16x16x32_bf16 v[78:81], v[160:163], v[218:221], v[78:81]
	v_mfma_f32_16x16x32_bf16 v[74:77], v[168:171], v[218:221], v[74:77]
	s_setprio 0
	s_barrier
; #define PG8_STAGE(bufoff, gbase, voff) do { _Pragma("unroll") for (int _i = 0; _i < 2; ++_i) \
;         __builtin_amdgcn_global_load_lds((const unsigned*)((const char*)(gbase) + (voff)[_i]), (PG8_LAS unsigned*)(lds + (bufoff) + ldsw + _i * 8192), 16, 0, 0); } while (0)
; #define PG8_LDA(dst, b, h) do { _Pragma("unroll") for (int m = 0; m < 4; ++m) _Pragma("unroll") for (int k = 0; k < 2; ++k) dst[m][k] = *(const PG8_LAS bf16x8*)(lds + PG8_SA(b, h) + aoff + m * 2048 + k * 1024); } while (0)
; #define PG8_MMA(ai, bj, At, Bt) do { __builtin_amdgcn_s_setprio(1); _Pragma("unroll") for (int m = 0; m < 4; ++m) _Pragma("unroll") for (int n = 0; n < 2; ++n) _Pragma("unroll") for (int k = 0; k < 2; ++k) \
;         acc[ai][bj][m][n] = __builtin_amdgcn_mfma_f32_16x16x32_bf16(Bt[n][k], At[m][k], acc[ai][bj][m][n], 0, 0, 0); __builtin_amdgcn_s_setprio(0); } while (0)
; #define PG8_WAIT_V(n) asm volatile("s_waitcnt vmcnt(" #n ")" ::: "memory")
; #define PG8_WAIT_L(n) asm volatile("s_waitcnt lgkmcnt(" #n ")" ::: "memory")
; #define PG8_BAR __builtin_amdgcn_s_barrier()
; #define PG8_SCHED __builtin_amdgcn_sched_barrier(0)
; template <class Epi, class Sched, bool ALIGN_EPI = false, bool SP2 = false>
; __device__ __forceinline__ void gemm_phase(PG8_LAS unsigned char* lds, const Gemm g, const Sched& S, const Epi& E) {
;     ...
;             PG8_LDA(At, 1, 1); PG8_STAGE(PG8_SB(1, 0), b3, voffB); PG8_STAGE(PG8_SB(1, 1), b3 + hstep, voffB); PG8_STAGE(PG8_SA(1, 0), a3, voffA);
;             PG8_WAIT_V(8); PG8_WAIT_L(0); PG8_BAR; PG8_MMA(1, 0, At, B0); PG8_MMA(1, 1, At, B1); PG8_BAR; PG8_SCHED;
;     ...
;         if constexpr (ALIGN_EPI) { if (wr == 0) PG8_BAR; }
	s_add_i32 s10, s10, s66
	v_lshl_add_u64 v[184:185], v[184:185], 0, s[44:45]
	s_mov_b32 m0, s10
	ds_read_b128 v[172:175], v207 offset:49152
	ds_read_b128 v[176:179], v207 offset:50176
	ds_read_b128 v[180:183], v207 offset:51200
	ds_read_b128 v[194:197], v207 offset:52224
	ds_read_b128 v[200:203], v207 offset:53248
	ds_read_b128 v[210:213], v207 offset:54272
	ds_read_b128 v[214:217], v207 offset:55296
	ds_read_b128 v[218:221], v207 offset:56320
	global_load_lds_dwordx4 v[184:185], off
	s_add_i32 m0, s10, 0x2000
	s_add_u32 s34, s62, 0x40080
	v_lshl_add_u64 v[184:185], v[222:223], 0, s[44:45]
	s_addc_u32 s35, s63, 0
	s_add_i32 s10, s11, s66
	global_load_lds_dwordx4 v[184:185], off
	v_lshl_add_u64 v[184:185], s[34:35], 0, v[142:143]
	s_mov_b32 m0, s10
	s_nop 0
	global_load_lds_dwordx4 v[184:185], off
	v_lshl_add_u64 v[184:185], s[34:35], 0, v[138:139]
	s_add_i32 m0, s10, 0x2000
	s_nop 0
	global_load_lds_dwordx4 v[184:185], off
	v_lshl_add_u64 v[184:185], v[232:233], 0, s[44:45]
	s_mov_b32 m0, s74
	s_nop 0
	global_load_lds_dwordx4 v[184:185], off
	v_lshl_add_u64 v[184:185], v[234:235], 0, s[44:45]
	s_mov_b32 m0, s75
	s_nop 0
	global_load_lds_dwordx4 v[184:185], off
	s_waitcnt vmcnt(8)
	s_waitcnt lgkmcnt(0)
	s_barrier
	s_setprio 1
	s_waitcnt lgkmcnt(0)
	v_mfma_f32_16x16x32_bf16 v[70:73], v[58:61], v[172:175], v[70:73]
	v_mfma_f32_16x16x32_bf16 v[66:69], v[148:151], v[172:175], v[66:69]
	v_mfma_f32_16x16x32_bf16 v[54:57], v[58:61], v[180:183], v[54:57]
	v_mfma_f32_16x16x32_bf16 v[50:53], v[148:151], v[180:183], v[50:53]
	v_mfma_f32_16x16x32_bf16 v[34:37], v[58:61], v[200:203], v[34:37]
	v_mfma_f32_16x16x32_bf16 v[30:33], v[148:151], v[200:203], v[30:33]
	v_mfma_f32_16x16x32_bf16 v[14:17], v[58:61], v[214:217], v[14:17]
	v_mfma_f32_16x16x32_bf16 v[10:13], v[148:151], v[214:217], v[10:13]
	v_mfma_f32_16x16x32_bf16 v[70:73], v[62:65], v[176:179], v[70:73]
	v_mfma_f32_16x16x32_bf16 v[66:69], v[152:155], v[176:179], v[66:69]
	v_mfma_f32_16x16x32_bf16 v[54:57], v[62:65], v[194:197], v[54:57]
	v_mfma_f32_16x16x32_bf16 v[50:53], v[152:155], v[194:197], v[50:53]
	v_mfma_f32_16x16x32_bf16 v[34:37], v[62:65], v[210:213], v[34:37]
	v_mfma_f32_16x16x32_bf16 v[30:33], v[152:155], v[210:213], v[30:33]
	v_mfma_f32_16x16x32_bf16 v[14:17], v[62:65], v[218:221], v[14:17]
	v_mfma_f32_16x16x32_bf16 v[10:13], v[152:155], v[218:221], v[10:13]
	v_mfma_f32_16x16x32_bf16 v[26:29], v[156:159], v[172:175], v[26:29]
	v_mfma_f32_16x16x32_bf16 v[62:65], v[160:163], v[176:179], v[26:29]
	v_mfma_f32_16x16x32_bf16 v[26:29], v[164:167], v[172:175], v[38:41]
	v_mfma_f32_16x16x32_bf16 v[58:61], v[168:171], v[176:179], v[26:29]
	v_mfma_f32_16x16x32_bf16 v[26:29], v[156:159], v[180:183], v[46:49]
	v_mfma_f32_16x16x32_bf16 v[46:49], v[160:163], v[194:197], v[26:29]
	v_mfma_f32_16x16x32_bf16 v[26:29], v[164:167], v[180:183], v[42:45]
	v_mfma_f32_16x16x32_bf16 v[22:25], v[156:159], v[200:203], v[22:25]
	v_mfma_f32_16x16x32_bf16 v[18:21], v[164:167], v[200:203], v[18:21]
	v_mfma_f32_16x16x32_bf16 v[6:9], v[156:159], v[214:217], v[6:9]
	v_mfma_f32_16x16x32_bf16 v[2:5], v[164:167], v[214:217], v[2:5]
	v_mfma_f32_16x16x32_bf16 v[42:45], v[168:171], v[194:197], v[26:29]
	v_mfma_f32_16x16x32_bf16 v[22:25], v[160:163], v[210:213], v[22:25]
	v_mfma_f32_16x16x32_bf16 v[18:21], v[168:171], v[210:213], v[18:21]
	v_mfma_f32_16x16x32_bf16 v[6:9], v[160:163], v[218:221], v[6:9]
	v_mfma_f32_16x16x32_bf16 v[2:5], v[168:171], v[218:221], v[2:5]
	s_setprio 0
	s_barrier
	s_add_i32 s59, s59, 2
	s_add_u32 s56, s56, 0x100
	s_addc_u32 s57, s57, 0
	s_add_u32 s51, s51, 0x100
	s_addc_u32 s53, s53, 0
	s_cmp_gt_u32 s59, 13
	s_cbranch_scc0 .LBB0_900
	s_and_b64 vcc, exec, s[48:49]
	s_cbranch_vccz .LBB0_903
	s_barrier
